# speedup vs baseline: 1.0528x; 1.0395x over previous
; #define LAS __attribute__((address_space(3)))
; #define TRY(W, K, N, WT, gain) { const int nt_ = ((K) / 64) * ((N) / 64); if (r >= 0 && r < nt_) { const int nb_ = (N) / 64; transpose_tile(W, K, N, WT, gain, (r / nb_) * 64, (r % nb_) * 64, tile, C.lane); } r -= nt_; }
; __device__ __forceinline__ void transpose_tile(const float* W, int K, int N, bf16* WT, const float* gain, int k0, int n0, LAS float* tile, int lane) {
;     f32x4 v[16];
; #pragma unroll
;     for (int pass = 0; pass < 16; ++pass) v[pass] = *(const f32x4*)(W + (size_t)(k0 + pass * 4 + (lane >> 4)) * N + n0 + (lane & 15) * 4);
; #pragma unroll
;     for (int pass = 0; pass < 16; ++pass) {
;         const int r = pass * 4 + (lane >> 4), c4 = (lane & 15) * 4;
;         const float g = gain ? gain[k0 + r] : 1.f;
;         tile[r * 65 + c4 + 0] = v[pass].x * g; tile[r * 65 + c4 + 1] = v[pass].y * g; tile[r * 65 + c4 + 2] = v[pass].z * g; tile[r * 65 + c4 + 3] = v[pass].w * g;
; __device__ __forceinline__ void p0_prologue(const Ctx& C) {
;     ...
;     for (int it = C.gw; it < 3392; it += C.NGW) {
;         int r = it;
;     ...
;         TRY(C.in[3], 1024, 2048, WSP(bf16, WS_WIN), C.in[2])
.LBB0_8:
	s_cmpk_gt_u32 s94, 0x1ff
	s_cbranch_scc1 .LBB0_34
	s_and_b32 s29, s83, 0x3c0
	s_and_b32 s28, s82, 0x7c0
	v_or_b32_e32 v101, s29, v1
	s_lshl_b32 s16, s28, 2
	v_lshl_add_u64 v[2:3], v[84:85], 0, s[16:17]
	v_lshlrev_b32_e32 v66, 13, v101
	v_lshl_add_u64 v[2:3], v[2:3], 0, v[66:67]
	v_add_co_u32_e32 v4, vcc, 0x8000, v2
	v_cndmask_b32_e64 v66, 0, 1, s[0:1]
	s_nop 0
	v_addc_co_u32_e32 v5, vcc, 0, v3, vcc
	global_load_dwordx4 v[62:65], v[2:3], off nt
	global_load_dwordx4 v[58:61], v[4:5], off nt
	v_add_co_u32_e32 v4, vcc, 0x10000, v2
	v_cmp_ne_u32_e64 s[2:3], 1, v66
	s_nop 0
	v_addc_co_u32_e32 v5, vcc, 0, v3, vcc
	v_add_co_u32_e32 v6, vcc, 0x18000, v2
	v_add_lshl_u32 v100, v1, s29, 2
	s_nop 0
	v_addc_co_u32_e32 v7, vcc, 0, v3, vcc
	global_load_dwordx4 v[54:57], v[4:5], off nt
	global_load_dwordx4 v[50:53], v[6:7], off nt
	v_add_co_u32_e32 v4, vcc, 0x20000, v2
	s_nop 1
	v_addc_co_u32_e32 v5, vcc, 0, v3, vcc
	v_add_co_u32_e32 v6, vcc, 0x28000, v2
	s_nop 1
	v_addc_co_u32_e32 v7, vcc, 0, v3, vcc
	global_load_dwordx4 v[46:49], v[4:5], off nt
	global_load_dwordx4 v[42:45], v[6:7], off nt
	v_add_co_u32_e32 v4, vcc, 0x30000, v2
	s_nop 1
	v_addc_co_u32_e32 v5, vcc, 0, v3, vcc
	v_add_co_u32_e32 v6, vcc, 0x38000, v2
	s_nop 1
	v_addc_co_u32_e32 v7, vcc, 0, v3, vcc
	global_load_dwordx4 v[38:41], v[4:5], off nt
	global_load_dwordx4 v[34:37], v[6:7], off nt
	v_add_co_u32_e32 v4, vcc, 0x40000, v2
	s_nop 1
	v_addc_co_u32_e32 v5, vcc, 0, v3, vcc
	v_add_co_u32_e32 v6, vcc, 0x48000, v2
	s_nop 1
	v_addc_co_u32_e32 v7, vcc, 0, v3, vcc
	global_load_dwordx4 v[30:33], v[4:5], off nt
	global_load_dwordx4 v[22:25], v[6:7], off nt
	v_add_co_u32_e32 v4, vcc, 0x50000, v2
	s_nop 1
	v_addc_co_u32_e32 v5, vcc, 0, v3, vcc
	v_add_co_u32_e32 v6, vcc, 0x58000, v2
	s_nop 1
	v_addc_co_u32_e32 v7, vcc, 0, v3, vcc
	v_add_co_u32_e32 v8, vcc, 0x60000, v2
	s_nop 1
	v_addc_co_u32_e32 v9, vcc, 0, v3, vcc
	v_add_co_u32_e32 v10, vcc, 0x68000, v2
	s_nop 1
	v_addc_co_u32_e32 v11, vcc, 0, v3, vcc
	v_add_co_u32_e32 v124, vcc, 0x70000, v2
	s_nop 1
	v_addc_co_u32_e32 v125, vcc, 0, v3, vcc
	v_add_co_u32_e32 v2, vcc, 0x78000, v2
	s_nop 1
	v_addc_co_u32_e32 v3, vcc, 0, v3, vcc
	global_load_dwordx4 v[26:29], v[4:5], off nt
	global_load_dwordx4 v[18:21], v[6:7], off nt
	global_load_dwordx4 v[14:17], v[8:9], off nt
	s_nop 0
	global_load_dwordx4 v[10:13], v[10:11], off nt
	s_nop 0
	global_load_dwordx4 v[6:9], v[124:125], off nt
	s_nop 0
	global_load_dwordx4 v[2:5], v[2:3], off nt
	s_andn2_b64 vcc, exec, s[0:1]
	s_cbranch_vccnz .LBB0_144
	v_lshlrev_b32_e32 v66, 2, v101
	global_load_dword v66, v66, s[64:65]
	s_waitcnt vmcnt(0)
	v_pk_mul_f32 v[124:125], v[62:63], v[66:67] op_sel_hi:[1,0]
	ds_write2_b32 v103, v124, v125 offset1:1
	v_pk_mul_f32 v[124:125], v[64:65], v[66:67] op_sel_hi:[1,0]
	global_load_dword v66, v100, s[64:65] offset:16
	ds_write2_b32 v103, v124, v125 offset0:2 offset1:3
	s_cbranch_execnz .LBB0_12

; #define LAS __attribute__((address_space(3)))
; __device__ __forceinline__ unsigned pk2(float lo, float hi) { f32x2_t v = {lo, hi}; bf16x2_t b = __builtin_convertvector(v, bf16x2_t); return __builtin_bit_cast(unsigned, b); }
; #define TRY(W, K, N, WT, gain) { const int nt_ = ((K) / 64) * ((N) / 64); if (r >= 0 && r < nt_) { const int nb_ = (N) / 64; transpose_tile(W, K, N, WT, gain, (r / nb_) * 64, (r % nb_) * 64, tile, C.lane); } r -= nt_; }
; __device__ __forceinline__ void transpose_tile(const float* W, int K, int N, bf16* WT, const float* gain, int k0, int n0, LAS float* tile, int lane) {
;     f32x4 v[16];
; #pragma unroll
;     for (int pass = 0; pass < 16; ++pass) v[pass] = *(const f32x4*)(W + (size_t)(k0 + pass * 4 + (lane >> 4)) * N + n0 + (lane & 15) * 4);
; #pragma unroll
;     for (int pass = 0; pass < 16; ++pass) {
;         const int r = pass * 4 + (lane >> 4), c4 = (lane & 15) * 4;
;         const float g = gain ? gain[k0 + r] : 1.f;
;         tile[r * 65 + c4 + 0] = v[pass].x * g; tile[r * 65 + c4 + 1] = v[pass].y * g; tile[r * 65 + c4 + 2] = v[pass].z * g; tile[r * 65 + c4 + 3] = v[pass].w * g;
;     }
;     asm volatile("s_waitcnt lgkmcnt(0)" ::: "memory"); __builtin_amdgcn_wave_barrier();
; #pragma unroll
;     for (int pass = 0; pass < 8; ++pass) {
;         const int n = pass * 8 + (lane >> 3), kc = (lane & 7) * 8;
;         float f[8];
; #pragma unroll
;         for (int q = 0; q < 8; ++q) f[q] = tile[(kc + q) * 65 + n];
;         u32x4 o; o.x = pk2(f[0], f[1]); o.y = pk2(f[2], f[3]); o.z = pk2(f[4], f[5]); o.w = pk2(f[6], f[7]);
;         *(u32x4*)(WT + (size_t)(n0 + n) * K + k0 + kc) = o;
;     }
;     asm volatile("s_waitcnt lgkmcnt(0)" ::: "memory"); __builtin_amdgcn_wave_barrier();
; __device__ __forceinline__ void p0_prologue(const Ctx& C) {
;     ...
;         TRY(C.in[12], 512, 512, WSP(bf16, WS_WGLU), (const float*)nullptr)
.LBB0_41:
	s_and_b32 s3, s84, 0x1c0
	s_and_b32 s2, s82, 0x1c0
	v_or_b32_e32 v4, s3, v1
	s_lshl_b32 s16, s2, 2
	v_lshl_add_u64 v[2:3], v[86:87], 0, s[16:17]
	v_lshlrev_b32_e32 v66, 11, v4
	v_lshl_add_u64 v[62:63], v[2:3], 0, v[66:67]
	v_add_co_u32_e32 v6, vcc, 0x2000, v62
	s_lshl_b32 s16, s3, 1
	s_nop 0
	v_addc_co_u32_e32 v7, vcc, 0, v63, vcc
	v_add_co_u32_e32 v10, vcc, 0x4000, v62
	global_load_dwordx4 v[2:5], v[62:63], off nt
	s_nop 0
	global_load_dwordx4 v[6:9], v[6:7], off nt
	v_addc_co_u32_e32 v11, vcc, 0, v63, vcc
	v_add_co_u32_e32 v14, vcc, 0x6000, v62
	s_nop 1
	v_addc_co_u32_e32 v15, vcc, 0, v63, vcc
	v_add_co_u32_e32 v18, vcc, s53, v62
	global_load_dwordx4 v[10:13], v[10:11], off nt
	s_nop 0
	global_load_dwordx4 v[14:17], v[14:15], off nt
	v_addc_co_u32_e32 v19, vcc, 0, v63, vcc
	v_add_co_u32_e32 v22, vcc, 0xa000, v62
	s_nop 1
	v_addc_co_u32_e32 v23, vcc, 0, v63, vcc
	v_add_co_u32_e32 v26, vcc, 0xc000, v62
	global_load_dwordx4 v[18:21], v[18:19], off nt
	s_nop 0
	global_load_dwordx4 v[22:25], v[22:23], off nt
	v_addc_co_u32_e32 v27, vcc, 0, v63, vcc
	v_add_co_u32_e32 v30, vcc, 0xe000, v62
	s_nop 1
	v_addc_co_u32_e32 v31, vcc, 0, v63, vcc
	v_add_co_u32_e32 v34, vcc, s54, v62
	global_load_dwordx4 v[26:29], v[26:27], off nt
	s_nop 0
	global_load_dwordx4 v[30:33], v[30:31], off nt
	v_addc_co_u32_e32 v35, vcc, 0, v63, vcc
	v_add_co_u32_e32 v38, vcc, 0x12000, v62
	s_nop 1
	v_addc_co_u32_e32 v39, vcc, 0, v63, vcc
	v_add_co_u32_e32 v42, vcc, 0x14000, v62
	global_load_dwordx4 v[34:37], v[34:35], off nt
	s_nop 0
	global_load_dwordx4 v[38:41], v[38:39], off nt
	v_addc_co_u32_e32 v43, vcc, 0, v63, vcc
	v_add_co_u32_e32 v46, vcc, 0x16000, v62
	s_nop 1
	v_addc_co_u32_e32 v47, vcc, 0, v63, vcc
	v_add_co_u32_e32 v50, vcc, s55, v62
	global_load_dwordx4 v[42:45], v[42:43], off nt
	s_nop 0
	global_load_dwordx4 v[46:49], v[46:47], off nt
	v_addc_co_u32_e32 v51, vcc, 0, v63, vcc
	v_add_co_u32_e32 v54, vcc, 0x1a000, v62
	s_nop 1
	v_addc_co_u32_e32 v55, vcc, 0, v63, vcc
	global_load_dwordx4 v[50:53], v[50:51], off nt
	s_nop 0
	global_load_dwordx4 v[54:57], v[54:55], off nt
	v_add_co_u32_e32 v58, vcc, 0x1c000, v62
	s_nop 1
	v_addc_co_u32_e32 v59, vcc, 0, v63, vcc
	global_load_dwordx4 v[58:61], v[58:59], off nt
	v_add_co_u32_e32 v62, vcc, 0x1e000, v62
	s_nop 1
	v_addc_co_u32_e32 v63, vcc, 0, v63, vcc
	global_load_dwordx4 v[62:65], v[62:63], off nt
	s_waitcnt vmcnt(15)
	ds_write2_b32 v103, v2, v3 offset1:1
	ds_write2_b32 v103, v4, v5 offset0:2 offset1:3
	s_waitcnt vmcnt(14)
	ds_write2_b32 v125, v6, v7 offset1:1
	ds_write2_b32 v126, v8, v9 offset1:1
	s_waitcnt vmcnt(13)
	ds_write2_b32 v127, v10, v11 offset1:1
	ds_write2_b32 v128, v12, v13 offset1:1
	s_waitcnt vmcnt(12)
	ds_write2_b32 v129, v14, v15 offset1:1
	ds_write2_b32 v130, v16, v17 offset1:1
	s_waitcnt vmcnt(11)
	ds_write2_b32 v131, v18, v19 offset1:1
	ds_write2_b32 v132, v20, v21 offset1:1
	s_waitcnt vmcnt(10)
	ds_write2_b32 v133, v22, v23 offset1:1
	ds_write2_b32 v134, v24, v25 offset1:1
	s_waitcnt vmcnt(9)
	ds_write2_b32 v135, v26, v27 offset1:1
	ds_write2_b32 v136, v28, v29 offset1:1
	s_waitcnt vmcnt(8)
	ds_write2_b32 v137, v30, v31 offset1:1
	ds_write2_b32 v138, v32, v33 offset1:1
	s_waitcnt vmcnt(7)
	ds_write2_b32 v139, v34, v35 offset1:1
	ds_write2_b32 v140, v36, v37 offset1:1
	s_waitcnt vmcnt(6)
	ds_write2_b32 v141, v38, v39 offset1:1
	ds_write2_b32 v142, v40, v41 offset1:1
	s_waitcnt vmcnt(5)
	ds_write2_b32 v143, v42, v43 offset1:1
	ds_write2_b32 v144, v44, v45 offset1:1
	s_waitcnt vmcnt(4)
	ds_write2_b32 v145, v46, v47 offset1:1
	ds_write2_b32 v146, v48, v49 offset1:1
	s_waitcnt vmcnt(3)
	ds_write2_b32 v147, v50, v51 offset1:1
	ds_write2_b32 v148, v52, v53 offset1:1
	s_waitcnt vmcnt(2)
	ds_write2_b32 v149, v54, v55 offset1:1
	ds_write2_b32 v150, v56, v57 offset1:1
	s_waitcnt vmcnt(1)
	ds_write2_b32 v151, v58, v59 offset1:1
	ds_write2_b32 v152, v60, v61 offset1:1
	s_waitcnt vmcnt(0)
	ds_write2_b32 v153, v62, v63 offset1:1
	ds_write2_b32 v154, v64, v65 offset1:1
	s_waitcnt lgkmcnt(0)
	ds_read2_b32 v[6:7], v116 offset0:65 offset1:73
	ds_read2_b32 v[8:9], v116 offset1:8
	ds_read2_b32 v[10:11], v116 offset0:130 offset1:138
	ds_read2_b32 v[12:13], v116 offset0:195 offset1:203
	ds_read2_b32 v[14:15], v124 offset0:4 offset1:12
	ds_read2_b32 v[16:17], v124 offset0:69 offset1:77
	ds_read2_b32 v[18:19], v124 offset0:134 offset1:142
	ds_read2_b32 v[20:21], v124 offset0:199 offset1:207
	s_waitcnt lgkmcnt(6)
	v_cvt_pk_bf16_f32 v2, v8, v6
	v_or_b32_e32 v6, s2, v115
	v_lshl_add_u64 v[22:23], v[70:71], 0, s[16:17]
	v_lshlrev_b32_e32 v66, 10, v6
	s_waitcnt lgkmcnt(4)
	v_cvt_pk_bf16_f32 v3, v10, v12
	s_waitcnt lgkmcnt(2)
	v_cvt_pk_bf16_f32 v4, v14, v16
	s_waitcnt lgkmcnt(0)
	v_cvt_pk_bf16_f32 v5, v18, v20
	v_lshl_add_u64 v[24:25], v[22:23], 0, v[66:67]
	global_store_dwordx4 v[24:25], v[2:5], off
	v_or_b32_e32 v6, s2, v117
	v_lshlrev_b32_e32 v66, 10, v6
	v_cvt_pk_bf16_f32 v2, v9, v7
	v_cvt_pk_bf16_f32 v3, v11, v13
	v_cvt_pk_bf16_f32 v4, v15, v17
	v_cvt_pk_bf16_f32 v5, v19, v21
	ds_read2_b32 v[8:9], v116 offset0:81 offset1:89
	ds_read2_b32 v[10:11], v116 offset0:16 offset1:24
	ds_read2_b32 v[12:13], v116 offset0:146 offset1:154
	ds_read2_b32 v[14:15], v116 offset0:211 offset1:219
	ds_read2_b32 v[16:17], v124 offset0:20 offset1:28
	ds_read2_b32 v[18:19], v124 offset0:85 offset1:93
	ds_read2_b32 v[20:21], v124 offset0:150 offset1:158
	ds_read2_b32 v[24:25], v124 offset0:215 offset1:223
	v_lshl_add_u64 v[6:7], v[22:23], 0, v[66:67]
	global_store_dwordx4 v[6:7], v[2:5], off
	v_or_b32_e32 v6, s2, v118
	v_lshlrev_b32_e32 v66, 10, v6
	s_waitcnt lgkmcnt(6)
	v_cvt_pk_bf16_f32 v2, v10, v8
	s_waitcnt lgkmcnt(4)
; __device__ __forceinline__ unsigned pk2(float lo, float hi) { f32x2_t v = {lo, hi}; bf16x2_t b = __builtin_convertvector(v, bf16x2_t); return __builtin_bit_cast(unsigned, b); }
; __device__ __forceinline__ void transpose_tile(const float* W, int K, int N, bf16* WT, const float* gain, int k0, int n0, LAS float* tile, int lane) {
;     ...
;     for (int pass = 0; pass < 8; ++pass) {
;         const int n = pass * 8 + (lane >> 3), kc = (lane & 7) * 8;
;         float f[8];
; #pragma unroll
;         for (int q = 0; q < 8; ++q) f[q] = tile[(kc + q) * 65 + n];
;         u32x4 o; o.x = pk2(f[0], f[1]); o.y = pk2(f[2], f[3]); o.z = pk2(f[4], f[5]); o.w = pk2(f[6], f[7]);
;         *(u32x4*)(WT + (size_t)(n0 + n) * K + k0 + kc) = o;
;     }
; __device__ __forceinline__ void p0_prologue(const Ctx& C) {
;     ...
;         { const int nt_ = 16 * 16; if (r >= 0 && r < nt_) { const int k0_ = (r / 16) * 64; transpose_tile(C.in[17], 1024, 1024, WSP(bf16, WS_W1), k0_ < 512 ? C.in[15] : C.in[16] - 512, k0_, (r % 16) * 64, tile, C.lane); } r -= nt_; }
	v_cvt_pk_bf16_f32 v3, v12, v14
	s_waitcnt lgkmcnt(2)
	v_cvt_pk_bf16_f32 v4, v16, v18
	s_waitcnt lgkmcnt(0)
	v_cvt_pk_bf16_f32 v5, v20, v24
	v_lshl_add_u64 v[6:7], v[22:23], 0, v[66:67]
	global_store_dwordx4 v[6:7], v[2:5], off
	v_or_b32_e32 v6, s2, v119
	v_lshlrev_b32_e32 v66, 10, v6
	v_cvt_pk_bf16_f32 v2, v11, v9
	v_cvt_pk_bf16_f32 v3, v13, v15
	v_cvt_pk_bf16_f32 v4, v17, v19
	v_cvt_pk_bf16_f32 v5, v21, v25
	ds_read2_b32 v[8:9], v116 offset0:32 offset1:40
	ds_read2_b32 v[10:11], v116 offset0:97 offset1:105
	ds_read2_b32 v[12:13], v116 offset0:162 offset1:170
	ds_read2_b32 v[14:15], v116 offset0:227 offset1:235
	ds_read2_b32 v[16:17], v124 offset0:36 offset1:44
	ds_read2_b32 v[18:19], v124 offset0:101 offset1:109
	ds_read2_b32 v[20:21], v124 offset0:166 offset1:174
	ds_read2_b32 v[24:25], v124 offset0:231 offset1:239
	v_lshl_add_u64 v[6:7], v[22:23], 0, v[66:67]
	global_store_dwordx4 v[6:7], v[2:5], off
	v_or_b32_e32 v6, s2, v120
	v_lshlrev_b32_e32 v66, 10, v6
	s_waitcnt lgkmcnt(6)
	v_cvt_pk_bf16_f32 v2, v8, v10
	s_waitcnt lgkmcnt(4)
	v_cvt_pk_bf16_f32 v3, v12, v14
	s_waitcnt lgkmcnt(2)
	v_cvt_pk_bf16_f32 v4, v16, v18
	s_waitcnt lgkmcnt(0)
	v_cvt_pk_bf16_f32 v5, v20, v24
	v_lshl_add_u64 v[6:7], v[22:23], 0, v[66:67]
	global_store_dwordx4 v[6:7], v[2:5], off
	v_or_b32_e32 v6, s2, v121
	v_lshlrev_b32_e32 v66, 10, v6
	v_cvt_pk_bf16_f32 v2, v9, v11
	v_cvt_pk_bf16_f32 v3, v13, v15
	v_cvt_pk_bf16_f32 v4, v17, v19
	v_cvt_pk_bf16_f32 v5, v21, v25
	ds_read2_b32 v[8:9], v116 offset0:48 offset1:56
	ds_read2_b32 v[10:11], v116 offset0:113 offset1:121
	ds_read2_b32 v[12:13], v116 offset0:178 offset1:186
	ds_read2_b32 v[14:15], v116 offset0:243 offset1:251
	ds_read2_b32 v[16:17], v124 offset0:52 offset1:60
	ds_read2_b32 v[18:19], v124 offset0:117 offset1:125
	ds_read2_b32 v[20:21], v124 offset0:182 offset1:190
	ds_read2_b32 v[24:25], v124 offset0:247 offset1:255
	v_lshl_add_u64 v[6:7], v[22:23], 0, v[66:67]
	global_store_dwordx4 v[6:7], v[2:5], off
	v_or_b32_e32 v6, s2, v122
	v_lshlrev_b32_e32 v66, 10, v6
	s_waitcnt lgkmcnt(6)
	v_cvt_pk_bf16_f32 v2, v8, v10
	s_waitcnt lgkmcnt(4)
	v_cvt_pk_bf16_f32 v3, v12, v14
	s_waitcnt lgkmcnt(2)
	v_cvt_pk_bf16_f32 v4, v16, v18
	s_waitcnt lgkmcnt(0)
	v_cvt_pk_bf16_f32 v5, v20, v24
	v_lshl_add_u64 v[6:7], v[22:23], 0, v[66:67]
	global_store_dwordx4 v[6:7], v[2:5], off
	v_or_b32_e32 v6, s2, v123
	v_lshlrev_b32_e32 v66, 10, v6
	v_cvt_pk_bf16_f32 v2, v9, v11
	v_cvt_pk_bf16_f32 v3, v13, v15
	v_cvt_pk_bf16_f32 v4, v17, v19
	v_cvt_pk_bf16_f32 v5, v21, v25
	v_lshl_add_u64 v[6:7], v[22:23], 0, v[66:67]
	global_store_dwordx4 v[6:7], v[2:5], off
	s_waitcnt lgkmcnt(0)
	s_add_i32 s2, s94, 0xfffffdc0
	s_cmpk_gt_u32 s2, 0xff
	s_cbranch_scc1 .LBB0_36
.LBB0_42:
	s_add_i32 s3, s30, 0x80001c00
	s_and_b32 s96, s3, 0x3c0
	s_cmpk_lt_u32 s2, 0x80
	s_cselect_b32 s25, s23, s35
	s_cselect_b32 s24, s22, s7
	s_and_b32 s95, s82, 0x3c0
	v_or_b32_e32 v101, s96, v1
	s_lshl_b32 s16, s95, 2
	v_lshl_add_u64 v[2:3], v[88:89], 0, s[16:17]
	v_lshlrev_b32_e32 v66, 12, v101
	v_lshl_add_u64 v[2:3], v[2:3], 0, v[66:67]
	v_add_co_u32_e32 v4, vcc, s86, v2
	s_cmp_lg_u64 s[24:25], 0
	s_nop 0
	v_addc_co_u32_e32 v5, vcc, 0, v3, vcc
	global_load_dwordx4 v[62:65], v[2:3], off nt
	global_load_dwordx4 v[58:61], v[4:5], off nt
	v_add_co_u32_e32 v4, vcc, s53, v2
	s_cselect_b64 s[28:29], -1, 0
	s_nop 0
	v_addc_co_u32_e32 v5, vcc, 0, v3, vcc
	v_add_co_u32_e32 v6, vcc, s87, v2
	s_cmp_eq_u64 s[24:25], 0
	s_nop 0
	v_addc_co_u32_e32 v7, vcc, 0, v3, vcc
	global_load_dwordx4 v[54:57], v[4:5], off nt
	global_load_dwordx4 v[50:53], v[6:7], off nt
	v_add_co_u32_e32 v4, vcc, s54, v2
	v_add_lshl_u32 v100, v1, s96, 2
	s_nop 0
	v_addc_co_u32_e32 v5, vcc, 0, v3, vcc
	v_add_co_u32_e32 v6, vcc, s91, v2
	s_nop 1
	v_addc_co_u32_e32 v7, vcc, 0, v3, vcc
	global_load_dwordx4 v[46:49], v[4:5], off nt
	global_load_dwordx4 v[42:45], v[6:7], off nt
	v_add_co_u32_e32 v4, vcc, s55, v2
	s_nop 1
	v_addc_co_u32_e32 v5, vcc, 0, v3, vcc
	v_add_co_u32_e32 v6, vcc, s92, v2
	s_nop 1
	v_addc_co_u32_e32 v7, vcc, 0, v3, vcc
	global_load_dwordx4 v[38:41], v[4:5], off nt
	global_load_dwordx4 v[34:37], v[6:7], off nt
	v_add_co_u32_e32 v4, vcc, s66, v2
	s_nop 1
	v_addc_co_u32_e32 v5, vcc, 0, v3, vcc
	v_add_co_u32_e32 v6, vcc, s93, v2
	s_nop 1
	v_addc_co_u32_e32 v7, vcc, 0, v3, vcc
	global_load_dwordx4 v[30:33], v[4:5], off nt
	global_load_dwordx4 v[26:29], v[6:7], off nt
	v_add_co_u32_e32 v4, vcc, s67, v2
	s_nop 1
	v_addc_co_u32_e32 v5, vcc, 0, v3, vcc
	v_add_co_u32_e32 v6, vcc, 0x2c000, v2
	s_nop 1
	v_addc_co_u32_e32 v7, vcc, 0, v3, vcc
	global_load_dwordx4 v[22:25], v[4:5], off nt
	global_load_dwordx4 v[18:21], v[6:7], off nt
	v_add_co_u32_e32 v4, vcc, s85, v2
	s_nop 1
	v_addc_co_u32_e32 v5, vcc, 0, v3, vcc
	v_add_co_u32_e32 v6, vcc, 0x34000, v2
	s_nop 1
	v_addc_co_u32_e32 v7, vcc, 0, v3, vcc
	global_load_dwordx4 v[14:17], v[4:5], off nt
	global_load_dwordx4 v[10:13], v[6:7], off nt
	v_add_co_u32_e32 v4, vcc, 0x38000, v2
	s_nop 1
	v_addc_co_u32_e32 v5, vcc, 0, v3, vcc
	v_add_co_u32_e32 v2, vcc, 0x3c000, v2
	s_nop 1
	v_addc_co_u32_e32 v3, vcc, 0, v3, vcc
	global_load_dwordx4 v[6:9], v[4:5], off nt
	s_nop 0
	global_load_dwordx4 v[2:5], v[2:3], off nt
	s_cbranch_scc1 .LBB0_152
	v_lshlrev_b32_e32 v66, 2, v101
	global_load_dword v158, v66, s[24:25]
	s_nop 0
	global_load_dword v66, v100, s[24:25] offset:16
	s_waitcnt vmcnt(1)
	v_pk_mul_f32 v[160:161], v[62:63], v[158:159] op_sel_hi:[1,0]
	v_pk_mul_f32 v[158:159], v[64:65], v[158:159] op_sel_hi:[1,0]
	ds_write2_b32 v103, v160, v161 offset1:1
	ds_write2_b32 v103, v158, v159 offset0:2 offset1:3
	s_cbranch_execnz .LBB0_45

; #define LAS __attribute__((address_space(3)))
; #define TRY(W, K, N, WT, gain) { const int nt_ = ((K) / 64) * ((N) / 64); if (r >= 0 && r < nt_) { const int nb_ = (N) / 64; transpose_tile(W, K, N, WT, gain, (r / nb_) * 64, (r % nb_) * 64, tile, C.lane); } r -= nt_; }
; __device__ __forceinline__ void transpose_tile(const float* W, int K, int N, bf16* WT, const float* gain, int k0, int n0, LAS float* tile, int lane) {
;     f32x4 v[16];
; #pragma unroll
;     for (int pass = 0; pass < 16; ++pass) v[pass] = *(const f32x4*)(W + (size_t)(k0 + pass * 4 + (lane >> 4)) * N + n0 + (lane & 15) * 4);
; #pragma unroll
;     for (int pass = 0; pass < 16; ++pass) {
;         const int r = pass * 4 + (lane >> 4), c4 = (lane & 15) * 4;
;         const float g = gain ? gain[k0 + r] : 1.f;
;         tile[r * 65 + c4 + 0] = v[pass].x * g; tile[r * 65 + c4 + 1] = v[pass].y * g; tile[r * 65 + c4 + 2] = v[pass].z * g; tile[r * 65 + c4 + 3] = v[pass].w * g;
; __device__ __forceinline__ void p0_prologue(const Ctx& C) {
;     ...
;         TRY(C.in[20], 1024, 512, WSP(bf16, WS_WQ), C.in[18])
.LBB0_67:
	s_add_i32 s2, s84, 0x7fffe600
	s_and_b32 s29, s2, 0x7fffffc0
	s_and_b32 s28, s82, 0x1c0
	v_or_b32_e32 v66, s29, v1
	s_lshl_b32 s16, s28, 2
	v_or_b32_e32 v6, 4, v66
	v_mov_b32_e32 v7, v67
	v_lshl_add_u64 v[2:3], v[90:91], 0, s[16:17]
	v_lshlrev_b64 v[4:5], 11, v[66:67]
	v_lshlrev_b64 v[6:7], 11, v[6:7]
	v_lshl_add_u64 v[4:5], v[2:3], 0, v[4:5]
	v_lshl_add_u64 v[6:7], v[2:3], 0, v[6:7]
	global_load_dwordx4 v[62:65], v[4:5], off nt
	global_load_dwordx4 v[58:61], v[6:7], off nt
	v_or_b32_e32 v4, 8, v66
	v_mov_b32_e32 v5, v67
	v_or_b32_e32 v6, 12, v66
	v_mov_b32_e32 v7, v67
	v_lshlrev_b64 v[4:5], 11, v[4:5]
	v_lshlrev_b64 v[6:7], 11, v[6:7]
	v_lshl_add_u64 v[4:5], v[2:3], 0, v[4:5]
	v_lshl_add_u64 v[6:7], v[2:3], 0, v[6:7]
	global_load_dwordx4 v[54:57], v[4:5], off nt
	global_load_dwordx4 v[50:53], v[6:7], off nt
	v_or_b32_e32 v4, 16, v66
	v_mov_b32_e32 v5, v67
	v_or_b32_e32 v6, 20, v66
	v_mov_b32_e32 v7, v67
	v_lshlrev_b64 v[4:5], 11, v[4:5]
	v_lshlrev_b64 v[6:7], 11, v[6:7]
	v_lshl_add_u64 v[4:5], v[2:3], 0, v[4:5]
	v_lshl_add_u64 v[6:7], v[2:3], 0, v[6:7]
	global_load_dwordx4 v[46:49], v[4:5], off nt
	global_load_dwordx4 v[42:45], v[6:7], off nt
	v_or_b32_e32 v4, 24, v66
	v_mov_b32_e32 v5, v67
	v_or_b32_e32 v6, 28, v66
	v_mov_b32_e32 v7, v67
	v_lshlrev_b64 v[4:5], 11, v[4:5]
	v_lshlrev_b64 v[6:7], 11, v[6:7]
	v_lshl_add_u64 v[4:5], v[2:3], 0, v[4:5]
	v_lshl_add_u64 v[6:7], v[2:3], 0, v[6:7]
	global_load_dwordx4 v[38:41], v[4:5], off nt
	global_load_dwordx4 v[34:37], v[6:7], off nt
	v_or_b32_e32 v4, 32, v66
	v_mov_b32_e32 v5, v67
	v_or_b32_e32 v6, 36, v66
	v_mov_b32_e32 v7, v67
	v_lshlrev_b64 v[4:5], 11, v[4:5]
	v_lshlrev_b64 v[6:7], 11, v[6:7]
	v_lshl_add_u64 v[4:5], v[2:3], 0, v[4:5]
	v_lshl_add_u64 v[6:7], v[2:3], 0, v[6:7]
	global_load_dwordx4 v[30:33], v[4:5], off nt
	global_load_dwordx4 v[26:29], v[6:7], off nt
	v_or_b32_e32 v4, 40, v66
	v_mov_b32_e32 v5, v67
	v_or_b32_e32 v6, 44, v66
	v_mov_b32_e32 v7, v67
	v_lshlrev_b64 v[4:5], 11, v[4:5]
	v_lshlrev_b64 v[6:7], 11, v[6:7]
	v_lshl_add_u64 v[4:5], v[2:3], 0, v[4:5]
	v_lshl_add_u64 v[6:7], v[2:3], 0, v[6:7]
	global_load_dwordx4 v[22:25], v[4:5], off nt
	global_load_dwordx4 v[18:21], v[6:7], off nt
	v_or_b32_e32 v4, 48, v66
	v_mov_b32_e32 v5, v67
	v_or_b32_e32 v6, 52, v66
	v_mov_b32_e32 v7, v67
	v_lshlrev_b64 v[4:5], 11, v[4:5]
	v_lshlrev_b64 v[6:7], 11, v[6:7]
	v_lshl_add_u64 v[4:5], v[2:3], 0, v[4:5]
	v_lshl_add_u64 v[6:7], v[2:3], 0, v[6:7]
	global_load_dwordx4 v[14:17], v[4:5], off nt
	global_load_dwordx4 v[10:13], v[6:7], off nt
	v_or_b32_e32 v4, 56, v66
	v_mov_b32_e32 v5, v67
	v_or_b32_e32 v6, 60, v66
	v_mov_b32_e32 v7, v67
	v_lshlrev_b64 v[4:5], 11, v[4:5]
	v_lshlrev_b64 v[6:7], 11, v[6:7]
	v_lshl_add_u64 v[4:5], v[2:3], 0, v[4:5]
	v_lshl_add_u64 v[2:3], v[2:3], 0, v[6:7]
	global_load_dwordx4 v[6:9], v[4:5], off nt
	s_nop 0
	global_load_dwordx4 v[2:5], v[2:3], off nt
	v_cndmask_b32_e64 v100, 0, 1, s[4:5]
	v_cmp_ne_u32_e64 s[2:3], 1, v100
	s_andn2_b64 vcc, exec, s[4:5]
	v_add_u32_e32 v100, s29, v1
	s_cbranch_vccnz .LBB0_160
	v_lshl_add_u64 v[158:159], v[66:67], 2, s[48:49]
	v_mov_b32_e32 v101, v67
	global_load_dword v158, v[158:159], off
	v_lshl_add_u64 v[160:161], v[100:101], 2, s[48:49]
	global_load_dword v66, v[160:161], off offset:16
	s_waitcnt vmcnt(1)
	v_pk_mul_f32 v[160:161], v[62:63], v[158:159] op_sel_hi:[1,0]
	v_pk_mul_f32 v[158:159], v[64:65], v[158:159] op_sel_hi:[1,0]
	ds_write2_b32 v103, v160, v161 offset1:1
	ds_write2_b32 v103, v158, v159 offset0:2 offset1:3
	s_cbranch_execnz .LBB0_70

; #define LAS __attribute__((address_space(3)))
; #define TRY(W, K, N, WT, gain) { const int nt_ = ((K) / 64) * ((N) / 64); if (r >= 0 && r < nt_) { const int nb_ = (N) / 64; transpose_tile(W, K, N, WT, gain, (r / nb_) * 64, (r % nb_) * 64, tile, C.lane); } r -= nt_; }
; __device__ __forceinline__ void transpose_tile(const float* W, int K, int N, bf16* WT, const float* gain, int k0, int n0, LAS float* tile, int lane) {
;     f32x4 v[16];
; #pragma unroll
;     for (int pass = 0; pass < 16; ++pass) v[pass] = *(const f32x4*)(W + (size_t)(k0 + pass * 4 + (lane >> 4)) * N + n0 + (lane & 15) * 4);
; #pragma unroll
;     for (int pass = 0; pass < 16; ++pass) {
;         const int r = pass * 4 + (lane >> 4), c4 = (lane & 15) * 4;
;         const float g = gain ? gain[k0 + r] : 1.f;
;         tile[r * 65 + c4 + 0] = v[pass].x * g; tile[r * 65 + c4 + 1] = v[pass].y * g; tile[r * 65 + c4 + 2] = v[pass].z * g; tile[r * 65 + c4 + 3] = v[pass].w * g;
; __device__ __forceinline__ void p0_prologue(const Ctx& C) {
;     ...
;         TRY(C.in[21], 1024, 1024, WSP(bf16, WS_WKV), C.in[19])
.LBB0_92:
	s_add_i32 s2, s30, 0x1600
	s_and_b32 s29, s2, 0x7fffffc0
	s_and_b32 s28, s82, 0x3c0
	v_or_b32_e32 v66, s29, v1
	s_lshl_b32 s16, s28, 2
	v_or_b32_e32 v6, 4, v66
	v_mov_b32_e32 v7, v67
	v_lshl_add_u64 v[2:3], v[92:93], 0, s[16:17]
	v_lshlrev_b64 v[4:5], 12, v[66:67]
	v_lshlrev_b64 v[6:7], 12, v[6:7]
	v_lshl_add_u64 v[4:5], v[2:3], 0, v[4:5]
	v_lshl_add_u64 v[6:7], v[2:3], 0, v[6:7]
	global_load_dwordx4 v[62:65], v[4:5], off nt
	global_load_dwordx4 v[58:61], v[6:7], off nt
	v_or_b32_e32 v4, 8, v66
	v_mov_b32_e32 v5, v67
	v_or_b32_e32 v6, 12, v66
	v_mov_b32_e32 v7, v67
	v_lshlrev_b64 v[4:5], 12, v[4:5]
	v_lshlrev_b64 v[6:7], 12, v[6:7]
	v_lshl_add_u64 v[4:5], v[2:3], 0, v[4:5]
	v_lshl_add_u64 v[6:7], v[2:3], 0, v[6:7]
	global_load_dwordx4 v[54:57], v[4:5], off nt
	global_load_dwordx4 v[50:53], v[6:7], off nt
	v_or_b32_e32 v4, 16, v66
	v_mov_b32_e32 v5, v67
	v_or_b32_e32 v6, 20, v66
	v_mov_b32_e32 v7, v67
	v_lshlrev_b64 v[4:5], 12, v[4:5]
	v_lshlrev_b64 v[6:7], 12, v[6:7]
	v_lshl_add_u64 v[4:5], v[2:3], 0, v[4:5]
	v_lshl_add_u64 v[6:7], v[2:3], 0, v[6:7]
	global_load_dwordx4 v[46:49], v[4:5], off nt
	global_load_dwordx4 v[42:45], v[6:7], off nt
	v_or_b32_e32 v4, 24, v66
	v_mov_b32_e32 v5, v67
	v_or_b32_e32 v6, 28, v66
	v_mov_b32_e32 v7, v67
	v_lshlrev_b64 v[4:5], 12, v[4:5]
	v_lshlrev_b64 v[6:7], 12, v[6:7]
	v_lshl_add_u64 v[4:5], v[2:3], 0, v[4:5]
	v_lshl_add_u64 v[6:7], v[2:3], 0, v[6:7]
	global_load_dwordx4 v[38:41], v[4:5], off nt
	global_load_dwordx4 v[34:37], v[6:7], off nt
	v_or_b32_e32 v4, 32, v66
	v_mov_b32_e32 v5, v67
	v_or_b32_e32 v6, 36, v66
	v_mov_b32_e32 v7, v67
	v_lshlrev_b64 v[4:5], 12, v[4:5]
	v_lshlrev_b64 v[6:7], 12, v[6:7]
	v_lshl_add_u64 v[4:5], v[2:3], 0, v[4:5]
	v_lshl_add_u64 v[6:7], v[2:3], 0, v[6:7]
	global_load_dwordx4 v[30:33], v[4:5], off nt
	global_load_dwordx4 v[26:29], v[6:7], off nt
	v_or_b32_e32 v4, 40, v66
	v_mov_b32_e32 v5, v67
	v_or_b32_e32 v6, 44, v66
	v_mov_b32_e32 v7, v67
	v_lshlrev_b64 v[4:5], 12, v[4:5]
	v_lshlrev_b64 v[6:7], 12, v[6:7]
	v_lshl_add_u64 v[4:5], v[2:3], 0, v[4:5]
	v_lshl_add_u64 v[6:7], v[2:3], 0, v[6:7]
	global_load_dwordx4 v[22:25], v[4:5], off nt
	global_load_dwordx4 v[18:21], v[6:7], off nt
	v_or_b32_e32 v4, 48, v66
	v_mov_b32_e32 v5, v67
	v_or_b32_e32 v6, 52, v66
	v_mov_b32_e32 v7, v67
	v_lshlrev_b64 v[4:5], 12, v[4:5]
	v_lshlrev_b64 v[6:7], 12, v[6:7]
	v_lshl_add_u64 v[4:5], v[2:3], 0, v[4:5]
	v_lshl_add_u64 v[6:7], v[2:3], 0, v[6:7]
	global_load_dwordx4 v[14:17], v[4:5], off nt
	global_load_dwordx4 v[10:13], v[6:7], off nt
	v_or_b32_e32 v4, 56, v66
	v_mov_b32_e32 v5, v67
	v_or_b32_e32 v6, 60, v66
	v_mov_b32_e32 v7, v67
	v_lshlrev_b64 v[4:5], 12, v[4:5]
	v_lshlrev_b64 v[6:7], 12, v[6:7]
	v_lshl_add_u64 v[4:5], v[2:3], 0, v[4:5]
	v_lshl_add_u64 v[2:3], v[2:3], 0, v[6:7]
	global_load_dwordx4 v[6:9], v[4:5], off nt
	s_nop 0
	global_load_dwordx4 v[2:5], v[2:3], off nt
	v_cndmask_b32_e64 v100, 0, 1, s[38:39]
	v_cmp_ne_u32_e64 s[2:3], 1, v100
	s_andn2_b64 vcc, exec, s[38:39]
	v_add_u32_e32 v100, s29, v1
	s_cbranch_vccnz .LBB0_168
	v_lshl_add_u64 v[158:159], v[66:67], 2, s[50:51]
	v_mov_b32_e32 v101, v67
	global_load_dword v158, v[158:159], off
	v_lshl_add_u64 v[160:161], v[100:101], 2, s[50:51]
	global_load_dword v66, v[160:161], off offset:16
	s_waitcnt vmcnt(1)
	v_pk_mul_f32 v[160:161], v[62:63], v[158:159] op_sel_hi:[1,0]
	v_pk_mul_f32 v[158:159], v[64:65], v[158:159] op_sel_hi:[1,0]
	ds_write2_b32 v103, v160, v161 offset1:1
	ds_write2_b32 v103, v158, v159 offset0:2 offset1:3
	s_cbranch_execnz .LBB0_95

; #define LAS __attribute__((address_space(3)))
; __device__ __forceinline__ unsigned pk2(float lo, float hi) { f32x2_t v = {lo, hi}; bf16x2_t b = __builtin_convertvector(v, bf16x2_t); return __builtin_bit_cast(unsigned, b); }
; #define TRY(W, K, N, WT, gain) { const int nt_ = ((K) / 64) * ((N) / 64); if (r >= 0 && r < nt_) { const int nb_ = (N) / 64; transpose_tile(W, K, N, WT, gain, (r / nb_) * 64, (r % nb_) * 64, tile, C.lane); } r -= nt_; }
; __device__ __forceinline__ void transpose_tile(const float* W, int K, int N, bf16* WT, const float* gain, int k0, int n0, LAS float* tile, int lane) {
;     f32x4 v[16];
; #pragma unroll
;     for (int pass = 0; pass < 16; ++pass) v[pass] = *(const f32x4*)(W + (size_t)(k0 + pass * 4 + (lane >> 4)) * N + n0 + (lane & 15) * 4);
; #pragma unroll
;     for (int pass = 0; pass < 16; ++pass) {
;         const int r = pass * 4 + (lane >> 4), c4 = (lane & 15) * 4;
;         const float g = gain ? gain[k0 + r] : 1.f;
;         tile[r * 65 + c4 + 0] = v[pass].x * g; tile[r * 65 + c4 + 1] = v[pass].y * g; tile[r * 65 + c4 + 2] = v[pass].z * g; tile[r * 65 + c4 + 3] = v[pass].w * g;
;     }
;     asm volatile("s_waitcnt lgkmcnt(0)" ::: "memory"); __builtin_amdgcn_wave_barrier();
; #pragma unroll
;     for (int pass = 0; pass < 8; ++pass) {
;         const int n = pass * 8 + (lane >> 3), kc = (lane & 7) * 8;
;         float f[8];
; #pragma unroll
;         for (int q = 0; q < 8; ++q) f[q] = tile[(kc + q) * 65 + n];
;         u32x4 o; o.x = pk2(f[0], f[1]); o.y = pk2(f[2], f[3]); o.z = pk2(f[4], f[5]); o.w = pk2(f[6], f[7]);
;         *(u32x4*)(WT + (size_t)(n0 + n) * K + k0 + kc) = o;
;     }
;     asm volatile("s_waitcnt lgkmcnt(0)" ::: "memory"); __builtin_amdgcn_wave_barrier();
; __device__ __forceinline__ void p0_prologue(const Ctx& C) {
;     ...
;         TRY(C.in[24], 512, 1024, WSP(bf16, WS_WO), (const float*)nullptr)
.LBB0_117:
	s_add_i32 s2, s30, 0x1200
	s_and_b32 s3, s2, 0x7fffffc0
	s_and_b32 s2, s82, 0x3c0
	v_or_b32_e32 v66, s3, v1
	s_lshl_b32 s16, s2, 2
	v_or_b32_e32 v4, 4, v66
	v_mov_b32_e32 v5, v67
	v_or_b32_e32 v10, 8, v66
	v_mov_b32_e32 v11, v67
	v_or_b32_e32 v12, 12, v66
	v_mov_b32_e32 v13, v67
	v_or_b32_e32 v18, 16, v66
	v_mov_b32_e32 v19, v67
	v_or_b32_e32 v20, 20, v66
	v_mov_b32_e32 v21, v67
	v_or_b32_e32 v26, 24, v66
	v_mov_b32_e32 v27, v67
	v_or_b32_e32 v28, 28, v66
	v_mov_b32_e32 v29, v67
	v_or_b32_e32 v34, 32, v66
	v_mov_b32_e32 v35, v67
	v_or_b32_e32 v36, 36, v66
	v_mov_b32_e32 v37, v67
	v_or_b32_e32 v42, 40, v66
	v_mov_b32_e32 v43, v67
	v_or_b32_e32 v44, 44, v66
	v_mov_b32_e32 v45, v67
	v_or_b32_e32 v50, 48, v66
	v_mov_b32_e32 v51, v67
	v_or_b32_e32 v52, 52, v66
	v_mov_b32_e32 v53, v67
	v_lshl_add_u64 v[62:63], v[94:95], 0, s[16:17]
	v_lshlrev_b64 v[2:3], 12, v[66:67]
	v_lshlrev_b64 v[4:5], 12, v[4:5]
	v_lshlrev_b64 v[10:11], 12, v[10:11]
	v_lshlrev_b64 v[12:13], 12, v[12:13]
	v_lshlrev_b64 v[18:19], 12, v[18:19]
	v_lshlrev_b64 v[20:21], 12, v[20:21]
	v_lshlrev_b64 v[26:27], 12, v[26:27]
	v_lshlrev_b64 v[28:29], 12, v[28:29]
	v_lshlrev_b64 v[34:35], 12, v[34:35]
	v_lshlrev_b64 v[36:37], 12, v[36:37]
	v_lshlrev_b64 v[42:43], 12, v[42:43]
	v_lshlrev_b64 v[44:45], 12, v[44:45]
	v_lshlrev_b64 v[50:51], 12, v[50:51]
	v_lshlrev_b64 v[52:53], 12, v[52:53]
	v_lshl_add_u64 v[2:3], v[62:63], 0, v[2:3]
	v_lshl_add_u64 v[6:7], v[62:63], 0, v[4:5]
	v_lshl_add_u64 v[10:11], v[62:63], 0, v[10:11]
	v_lshl_add_u64 v[14:15], v[62:63], 0, v[12:13]
	v_lshl_add_u64 v[18:19], v[62:63], 0, v[18:19]
	v_lshl_add_u64 v[22:23], v[62:63], 0, v[20:21]
	v_lshl_add_u64 v[26:27], v[62:63], 0, v[26:27]
	v_lshl_add_u64 v[30:31], v[62:63], 0, v[28:29]
	v_lshl_add_u64 v[34:35], v[62:63], 0, v[34:35]
	v_lshl_add_u64 v[38:39], v[62:63], 0, v[36:37]
	v_lshl_add_u64 v[42:43], v[62:63], 0, v[42:43]
	v_lshl_add_u64 v[46:47], v[62:63], 0, v[44:45]
	v_lshl_add_u64 v[50:51], v[62:63], 0, v[50:51]
	v_lshl_add_u64 v[54:55], v[62:63], 0, v[52:53]
	global_load_dwordx4 v[2:5], v[2:3], off nt
	s_nop 0
	global_load_dwordx4 v[6:9], v[6:7], off nt
	s_nop 0
	global_load_dwordx4 v[10:13], v[10:11], off nt
	s_nop 0
	global_load_dwordx4 v[14:17], v[14:15], off nt
	s_nop 0
	global_load_dwordx4 v[18:21], v[18:19], off nt
	s_nop 0
	global_load_dwordx4 v[22:25], v[22:23], off nt
	s_nop 0
	global_load_dwordx4 v[26:29], v[26:27], off nt
	s_nop 0
	global_load_dwordx4 v[30:33], v[30:31], off nt
	s_nop 0
	global_load_dwordx4 v[34:37], v[34:35], off nt
	s_nop 0
	global_load_dwordx4 v[38:41], v[38:39], off nt
	s_nop 0
	global_load_dwordx4 v[42:45], v[42:43], off nt
	s_nop 0
	global_load_dwordx4 v[46:49], v[46:47], off nt
	s_nop 0
	global_load_dwordx4 v[50:53], v[50:51], off nt
	s_nop 0
	global_load_dwordx4 v[54:57], v[54:55], off nt
	v_or_b32_e32 v58, 56, v66
	v_mov_b32_e32 v59, v67
	v_lshlrev_b64 v[58:59], 12, v[58:59]
	v_lshl_add_u64 v[58:59], v[62:63], 0, v[58:59]
	v_or_b32_e32 v66, 60, v66
	global_load_dwordx4 v[58:61], v[58:59], off nt
	v_lshlrev_b64 v[64:65], 12, v[66:67]
	v_lshl_add_u64 v[62:63], v[62:63], 0, v[64:65]
	global_load_dwordx4 v[62:65], v[62:63], off nt
	s_lshl_b32 s16, s3, 1
	s_waitcnt vmcnt(15)
	ds_write2_b32 v103, v2, v3 offset1:1
	ds_write2_b32 v103, v4, v5 offset0:2 offset1:3
	s_waitcnt vmcnt(14)
	ds_write2_b32 v125, v6, v7 offset1:1
	ds_write2_b32 v126, v8, v9 offset1:1
	s_waitcnt vmcnt(13)
	ds_write2_b32 v127, v10, v11 offset1:1
	ds_write2_b32 v128, v12, v13 offset1:1
	s_waitcnt vmcnt(12)
	ds_write2_b32 v129, v14, v15 offset1:1
	ds_write2_b32 v130, v16, v17 offset1:1
	s_waitcnt vmcnt(11)
	ds_write2_b32 v131, v18, v19 offset1:1
	ds_write2_b32 v132, v20, v21 offset1:1
	s_waitcnt vmcnt(10)
	ds_write2_b32 v133, v22, v23 offset1:1
	ds_write2_b32 v134, v24, v25 offset1:1
	s_waitcnt vmcnt(9)
	ds_write2_b32 v135, v26, v27 offset1:1
	ds_write2_b32 v136, v28, v29 offset1:1
	s_waitcnt vmcnt(8)
	ds_write2_b32 v137, v30, v31 offset1:1
	ds_write2_b32 v138, v32, v33 offset1:1
	s_waitcnt vmcnt(7)
	ds_write2_b32 v139, v34, v35 offset1:1
	ds_write2_b32 v140, v36, v37 offset1:1
	s_waitcnt vmcnt(6)
	ds_write2_b32 v141, v38, v39 offset1:1
	ds_write2_b32 v142, v40, v41 offset1:1
	s_waitcnt vmcnt(5)
	ds_write2_b32 v143, v42, v43 offset1:1
	ds_write2_b32 v144, v44, v45 offset1:1
	s_waitcnt vmcnt(4)
	ds_write2_b32 v145, v46, v47 offset1:1
	ds_write2_b32 v146, v48, v49 offset1:1
	s_waitcnt vmcnt(3)
	ds_write2_b32 v147, v50, v51 offset1:1
	ds_write2_b32 v148, v52, v53 offset1:1
	s_waitcnt vmcnt(2)
	ds_write2_b32 v149, v54, v55 offset1:1
	ds_write2_b32 v150, v56, v57 offset1:1
	s_waitcnt vmcnt(1)
	ds_write2_b32 v151, v58, v59 offset1:1
	ds_write2_b32 v152, v60, v61 offset1:1
	s_waitcnt vmcnt(0)
	ds_write2_b32 v153, v62, v63 offset1:1
	ds_write2_b32 v154, v64, v65 offset1:1
	s_waitcnt lgkmcnt(0)
	ds_read2_b32 v[6:7], v116 offset0:65 offset1:73
	ds_read2_b32 v[8:9], v116 offset1:8
	ds_read2_b32 v[10:11], v116 offset0:130 offset1:138
	ds_read2_b32 v[12:13], v116 offset0:195 offset1:203
	ds_read2_b32 v[14:15], v124 offset0:4 offset1:12
	ds_read2_b32 v[16:17], v124 offset0:69 offset1:77
	ds_read2_b32 v[18:19], v124 offset0:134 offset1:142
	ds_read2_b32 v[20:21], v124 offset0:199 offset1:207
	s_waitcnt lgkmcnt(6)
	v_cvt_pk_bf16_f32 v2, v8, v6
	v_or_b32_e32 v6, s2, v115
	v_lshl_add_u64 v[22:23], v[78:79], 0, s[16:17]
	v_lshlrev_b32_e32 v66, 10, v6
	s_waitcnt lgkmcnt(4)
	v_cvt_pk_bf16_f32 v3, v10, v12
	s_waitcnt lgkmcnt(2)
	v_cvt_pk_bf16_f32 v4, v14, v16
	s_waitcnt lgkmcnt(0)
; __device__ __forceinline__ unsigned pk2(float lo, float hi) { f32x2_t v = {lo, hi}; bf16x2_t b = __builtin_convertvector(v, bf16x2_t); return __builtin_bit_cast(unsigned, b); }
; #define TRY(W, K, N, WT, gain) { const int nt_ = ((K) / 64) * ((N) / 64); if (r >= 0 && r < nt_) { const int nb_ = (N) / 64; transpose_tile(W, K, N, WT, gain, (r / nb_) * 64, (r % nb_) * 64, tile, C.lane); } r -= nt_; }
; __device__ __forceinline__ void transpose_tile(const float* W, int K, int N, bf16* WT, const float* gain, int k0, int n0, LAS float* tile, int lane) {
;     ...
;     for (int pass = 0; pass < 8; ++pass) {
;         const int n = pass * 8 + (lane >> 3), kc = (lane & 7) * 8;
;         float f[8];
; #pragma unroll
;         for (int q = 0; q < 8; ++q) f[q] = tile[(kc + q) * 65 + n];
;         u32x4 o; o.x = pk2(f[0], f[1]); o.y = pk2(f[2], f[3]); o.z = pk2(f[4], f[5]); o.w = pk2(f[6], f[7]);
;         *(u32x4*)(WT + (size_t)(n0 + n) * K + k0 + kc) = o;
;     }
; __device__ __forceinline__ void p0_prologue(const Ctx& C) {
;     ...
;         TRY(C.in[26], 1024, 4096, WSP(bf16, WS_WUP), C.in[25])
	v_cvt_pk_bf16_f32 v5, v18, v20
	v_lshl_add_u64 v[24:25], v[22:23], 0, v[66:67]
	global_store_dwordx4 v[24:25], v[2:5], off
	v_or_b32_e32 v6, s2, v117
	v_lshlrev_b32_e32 v66, 10, v6
	v_cvt_pk_bf16_f32 v2, v9, v7
	v_cvt_pk_bf16_f32 v3, v11, v13
	v_cvt_pk_bf16_f32 v4, v15, v17
	v_cvt_pk_bf16_f32 v5, v19, v21
	ds_read2_b32 v[8:9], v116 offset0:81 offset1:89
	ds_read2_b32 v[10:11], v116 offset0:16 offset1:24
	ds_read2_b32 v[12:13], v116 offset0:146 offset1:154
	ds_read2_b32 v[14:15], v116 offset0:211 offset1:219
	ds_read2_b32 v[16:17], v124 offset0:20 offset1:28
	ds_read2_b32 v[18:19], v124 offset0:85 offset1:93
	ds_read2_b32 v[20:21], v124 offset0:150 offset1:158
	ds_read2_b32 v[24:25], v124 offset0:215 offset1:223
	v_lshl_add_u64 v[6:7], v[22:23], 0, v[66:67]
	global_store_dwordx4 v[6:7], v[2:5], off
	v_or_b32_e32 v6, s2, v118
	v_lshlrev_b32_e32 v66, 10, v6
	s_waitcnt lgkmcnt(6)
	v_cvt_pk_bf16_f32 v2, v10, v8
	s_waitcnt lgkmcnt(4)
	v_cvt_pk_bf16_f32 v3, v12, v14
	s_waitcnt lgkmcnt(2)
	v_cvt_pk_bf16_f32 v4, v16, v18
	s_waitcnt lgkmcnt(0)
	v_cvt_pk_bf16_f32 v5, v20, v24
	v_lshl_add_u64 v[6:7], v[22:23], 0, v[66:67]
	global_store_dwordx4 v[6:7], v[2:5], off
	v_or_b32_e32 v6, s2, v119
	v_lshlrev_b32_e32 v66, 10, v6
	v_cvt_pk_bf16_f32 v2, v11, v9
	v_cvt_pk_bf16_f32 v3, v13, v15
	v_cvt_pk_bf16_f32 v4, v17, v19
	v_cvt_pk_bf16_f32 v5, v21, v25
	ds_read2_b32 v[8:9], v116 offset0:32 offset1:40
	ds_read2_b32 v[10:11], v116 offset0:97 offset1:105
	ds_read2_b32 v[12:13], v116 offset0:162 offset1:170
	ds_read2_b32 v[14:15], v116 offset0:227 offset1:235
	ds_read2_b32 v[16:17], v124 offset0:36 offset1:44
	ds_read2_b32 v[18:19], v124 offset0:101 offset1:109
	ds_read2_b32 v[20:21], v124 offset0:166 offset1:174
	ds_read2_b32 v[24:25], v124 offset0:231 offset1:239
	v_lshl_add_u64 v[6:7], v[22:23], 0, v[66:67]
	global_store_dwordx4 v[6:7], v[2:5], off
	v_or_b32_e32 v6, s2, v120
	v_lshlrev_b32_e32 v66, 10, v6
	s_waitcnt lgkmcnt(6)
	v_cvt_pk_bf16_f32 v2, v8, v10
	s_waitcnt lgkmcnt(4)
	v_cvt_pk_bf16_f32 v3, v12, v14
	s_waitcnt lgkmcnt(2)
	v_cvt_pk_bf16_f32 v4, v16, v18
	s_waitcnt lgkmcnt(0)
	v_cvt_pk_bf16_f32 v5, v20, v24
	v_lshl_add_u64 v[6:7], v[22:23], 0, v[66:67]
	global_store_dwordx4 v[6:7], v[2:5], off
	v_or_b32_e32 v6, s2, v121
	v_lshlrev_b32_e32 v66, 10, v6
	v_cvt_pk_bf16_f32 v2, v9, v11
	v_cvt_pk_bf16_f32 v3, v13, v15
	v_cvt_pk_bf16_f32 v4, v17, v19
	v_cvt_pk_bf16_f32 v5, v21, v25
	ds_read2_b32 v[8:9], v116 offset0:48 offset1:56
	ds_read2_b32 v[10:11], v116 offset0:113 offset1:121
	ds_read2_b32 v[12:13], v116 offset0:178 offset1:186
	ds_read2_b32 v[14:15], v116 offset0:243 offset1:251
	ds_read2_b32 v[16:17], v124 offset0:52 offset1:60
	ds_read2_b32 v[18:19], v124 offset0:117 offset1:125
	ds_read2_b32 v[20:21], v124 offset0:182 offset1:190
	ds_read2_b32 v[24:25], v124 offset0:247 offset1:255
	v_lshl_add_u64 v[6:7], v[22:23], 0, v[66:67]
	global_store_dwordx4 v[6:7], v[2:5], off
	v_or_b32_e32 v6, s2, v122
	v_lshlrev_b32_e32 v66, 10, v6
	s_waitcnt lgkmcnt(6)
	v_cvt_pk_bf16_f32 v2, v8, v10
	s_waitcnt lgkmcnt(4)
	v_cvt_pk_bf16_f32 v3, v12, v14
	s_waitcnt lgkmcnt(2)
	v_cvt_pk_bf16_f32 v4, v16, v18
	s_waitcnt lgkmcnt(0)
	v_cvt_pk_bf16_f32 v5, v20, v24
	v_lshl_add_u64 v[6:7], v[22:23], 0, v[66:67]
	global_store_dwordx4 v[6:7], v[2:5], off
	v_or_b32_e32 v6, s2, v123
	v_lshlrev_b32_e32 v66, 10, v6
	v_cvt_pk_bf16_f32 v2, v9, v11
	v_cvt_pk_bf16_f32 v3, v13, v15
	v_cvt_pk_bf16_f32 v4, v17, v19
	v_cvt_pk_bf16_f32 v5, v21, v25
	v_lshl_add_u64 v[6:7], v[22:23], 0, v[66:67]
	global_store_dwordx4 v[6:7], v[2:5], off
	s_waitcnt lgkmcnt(0)
	s_add_i32 s2, s94, 0xfffffac0
	s_cmpk_gt_u32 s2, 0x3ff
	s_cbranch_scc1 .LBB0_40
; #define LAS __attribute__((address_space(3)))
; #define TRY(W, K, N, WT, gain) { const int nt_ = ((K) / 64) * ((N) / 64); if (r >= 0 && r < nt_) { const int nb_ = (N) / 64; transpose_tile(W, K, N, WT, gain, (r / nb_) * 64, (r % nb_) * 64, tile, C.lane); } r -= nt_; }
; __device__ __forceinline__ void transpose_tile(const float* W, int K, int N, bf16* WT, const float* gain, int k0, int n0, LAS float* tile, int lane) {
;     f32x4 v[16];
; #pragma unroll
;     for (int pass = 0; pass < 16; ++pass) v[pass] = *(const f32x4*)(W + (size_t)(k0 + pass * 4 + (lane >> 4)) * N + n0 + (lane & 15) * 4);
; #pragma unroll
;     for (int pass = 0; pass < 16; ++pass) {
;         const int r = pass * 4 + (lane >> 4), c4 = (lane & 15) * 4;
;         const float g = gain ? gain[k0 + r] : 1.f;
;         tile[r * 65 + c4 + 0] = v[pass].x * g; tile[r * 65 + c4 + 1] = v[pass].y * g; tile[r * 65 + c4 + 2] = v[pass].z * g; tile[r * 65 + c4 + 3] = v[pass].w * g;
; __device__ __forceinline__ void p0_prologue(const Ctx& C) {
;     ...
;         TRY(C.in[26], 1024, 4096, WSP(bf16, WS_WUP), C.in[25])
.LBB0_118:
	s_and_b32 s2, s94, 0xfc0
	s_add_i32 s16, s2, 0xfffffac0
	s_and_b32 s28, s82, 0xfc0
	v_or_b32_e32 v66, s16, v1
	s_lshl_b32 s2, s28, 2
	s_mov_b32 s3, s17
	v_or_b32_e32 v6, 4, v66
	v_mov_b32_e32 v7, v67
	v_lshl_add_u64 v[2:3], v[96:97], 0, s[2:3]
	v_lshlrev_b64 v[4:5], 14, v[66:67]
	v_lshlrev_b64 v[6:7], 14, v[6:7]
	v_lshl_add_u64 v[4:5], v[2:3], 0, v[4:5]
	v_lshl_add_u64 v[6:7], v[2:3], 0, v[6:7]
	global_load_dwordx4 v[62:65], v[4:5], off nt
	global_load_dwordx4 v[58:61], v[6:7], off nt
	v_or_b32_e32 v4, 8, v66
	v_mov_b32_e32 v5, v67
	v_or_b32_e32 v6, 12, v66
	v_mov_b32_e32 v7, v67
	v_lshlrev_b64 v[4:5], 14, v[4:5]
	v_lshlrev_b64 v[6:7], 14, v[6:7]
	v_lshl_add_u64 v[4:5], v[2:3], 0, v[4:5]
	v_lshl_add_u64 v[6:7], v[2:3], 0, v[6:7]
	global_load_dwordx4 v[54:57], v[4:5], off nt
	global_load_dwordx4 v[50:53], v[6:7], off nt
	v_or_b32_e32 v4, 16, v66
	v_mov_b32_e32 v5, v67
	v_or_b32_e32 v6, 20, v66
	v_mov_b32_e32 v7, v67
	v_lshlrev_b64 v[4:5], 14, v[4:5]
	v_lshlrev_b64 v[6:7], 14, v[6:7]
	v_lshl_add_u64 v[4:5], v[2:3], 0, v[4:5]
	v_lshl_add_u64 v[6:7], v[2:3], 0, v[6:7]
	global_load_dwordx4 v[46:49], v[4:5], off nt
	global_load_dwordx4 v[42:45], v[6:7], off nt
	v_or_b32_e32 v4, 24, v66
	v_mov_b32_e32 v5, v67
	v_or_b32_e32 v6, 28, v66
	v_mov_b32_e32 v7, v67
	v_lshlrev_b64 v[4:5], 14, v[4:5]
	v_lshlrev_b64 v[6:7], 14, v[6:7]
	v_lshl_add_u64 v[4:5], v[2:3], 0, v[4:5]
	v_lshl_add_u64 v[6:7], v[2:3], 0, v[6:7]
	global_load_dwordx4 v[38:41], v[4:5], off nt
	global_load_dwordx4 v[34:37], v[6:7], off nt
	v_or_b32_e32 v4, 32, v66
	v_mov_b32_e32 v5, v67
	v_or_b32_e32 v6, 36, v66
	v_mov_b32_e32 v7, v67
	v_lshlrev_b64 v[4:5], 14, v[4:5]
	v_lshlrev_b64 v[6:7], 14, v[6:7]
	v_lshl_add_u64 v[4:5], v[2:3], 0, v[4:5]
	v_lshl_add_u64 v[6:7], v[2:3], 0, v[6:7]
	global_load_dwordx4 v[30:33], v[4:5], off nt
	global_load_dwordx4 v[26:29], v[6:7], off nt
	v_or_b32_e32 v4, 40, v66
	v_mov_b32_e32 v5, v67
	v_or_b32_e32 v6, 44, v66
	v_mov_b32_e32 v7, v67
	v_lshlrev_b64 v[4:5], 14, v[4:5]
	v_lshlrev_b64 v[6:7], 14, v[6:7]
	v_lshl_add_u64 v[4:5], v[2:3], 0, v[4:5]
	v_lshl_add_u64 v[6:7], v[2:3], 0, v[6:7]
	global_load_dwordx4 v[22:25], v[4:5], off nt
	global_load_dwordx4 v[18:21], v[6:7], off nt
	v_or_b32_e32 v4, 48, v66
	v_mov_b32_e32 v5, v67
	v_or_b32_e32 v6, 52, v66
	v_mov_b32_e32 v7, v67
	v_lshlrev_b64 v[4:5], 14, v[4:5]
	v_lshlrev_b64 v[6:7], 14, v[6:7]
	v_lshl_add_u64 v[4:5], v[2:3], 0, v[4:5]
	v_lshl_add_u64 v[6:7], v[2:3], 0, v[6:7]
	global_load_dwordx4 v[14:17], v[4:5], off nt
	global_load_dwordx4 v[10:13], v[6:7], off nt
	v_or_b32_e32 v4, 56, v66
	v_mov_b32_e32 v5, v67
	v_or_b32_e32 v6, 60, v66
	v_mov_b32_e32 v7, v67
	v_lshlrev_b64 v[4:5], 14, v[4:5]
	v_lshlrev_b64 v[6:7], 14, v[6:7]
	v_lshl_add_u64 v[4:5], v[2:3], 0, v[4:5]
	v_lshl_add_u64 v[2:3], v[2:3], 0, v[6:7]
	global_load_dwordx4 v[6:9], v[4:5], off nt
	s_nop 0
	global_load_dwordx4 v[2:5], v[2:3], off nt
	v_cndmask_b32_e64 v100, 0, 1, s[44:45]
	v_cmp_ne_u32_e64 s[2:3], 1, v100
	s_andn2_b64 vcc, exec, s[44:45]
	v_add_u32_e32 v100, s16, v1
	s_cbranch_vccnz .LBB0_176
	v_lshl_add_u64 v[158:159], v[66:67], 2, s[26:27]
	v_mov_b32_e32 v101, v67
	global_load_dword v158, v[158:159], off
	v_lshl_add_u64 v[160:161], v[100:101], 2, s[26:27]
	global_load_dword v66, v[160:161], off offset:16
	s_waitcnt vmcnt(1)
	v_pk_mul_f32 v[160:161], v[62:63], v[158:159] op_sel_hi:[1,0]
	v_pk_mul_f32 v[158:159], v[64:65], v[158:159] op_sel_hi:[1,0]
	ds_write2_b32 v103, v160, v161 offset1:1
	ds_write2_b32 v103, v158, v159 offset0:2 offset1:3
	s_cbranch_execnz .LBB0_121

; #define LAS __attribute__((address_space(3)))
; #define TRY(W, K, N, WT, gain) { const int nt_ = ((K) / 64) * ((N) / 64); if (r >= 0 && r < nt_) { const int nb_ = (N) / 64; transpose_tile(W, K, N, WT, gain, (r / nb_) * 64, (r % nb_) * 64, tile, C.lane); } r -= nt_; }
; __device__ __forceinline__ void transpose_tile(const float* W, int K, int N, bf16* WT, const float* gain, int k0, int n0, LAS float* tile, int lane) {
;     f32x4 v[16];
; #pragma unroll
;     for (int pass = 0; pass < 16; ++pass) v[pass] = *(const f32x4*)(W + (size_t)(k0 + pass * 4 + (lane >> 4)) * N + n0 + (lane & 15) * 4);
; #pragma unroll
;     for (int pass = 0; pass < 16; ++pass) {
;         const int r = pass * 4 + (lane >> 4), c4 = (lane & 15) * 4;
;         const float g = gain ? gain[k0 + r] : 1.f;
;         tile[r * 65 + c4 + 0] = v[pass].x * g; tile[r * 65 + c4 + 1] = v[pass].y * g; tile[r * 65 + c4 + 2] = v[pass].z * g; tile[r * 65 + c4 + 3] = v[pass].w * g;
; __device__ __forceinline__ void p0_prologue(const Ctx& C) {
;     ...
;         TRY(C.in[27], 4096, 1024, WSP(bf16, WS_WDN), (const float*)nullptr)
.LBB0_143:
	s_and_b32 s3, s30, 0x7fffffc0
	s_and_b32 s2, s82, 0x3c0
	v_or_b32_e32 v66, s3, v1
	s_lshl_b32 s16, s2, 2
	v_or_b32_e32 v4, 4, v66
	v_mov_b32_e32 v5, v67
	v_or_b32_e32 v10, 8, v66
	v_mov_b32_e32 v11, v67
	v_or_b32_e32 v12, 12, v66
	v_mov_b32_e32 v13, v67
	v_or_b32_e32 v18, 16, v66
	v_mov_b32_e32 v19, v67
	v_or_b32_e32 v20, 20, v66
	v_mov_b32_e32 v21, v67
	v_or_b32_e32 v26, 24, v66
	v_mov_b32_e32 v27, v67
	v_or_b32_e32 v28, 28, v66
	v_mov_b32_e32 v29, v67
	v_or_b32_e32 v34, 32, v66
	v_mov_b32_e32 v35, v67
	v_or_b32_e32 v36, 36, v66
	v_mov_b32_e32 v37, v67
	v_or_b32_e32 v42, 40, v66
	v_mov_b32_e32 v43, v67
	v_or_b32_e32 v44, 44, v66
	v_mov_b32_e32 v45, v67
	v_or_b32_e32 v50, 48, v66
	v_mov_b32_e32 v51, v67
	v_or_b32_e32 v52, 52, v66
	v_mov_b32_e32 v53, v67
	v_lshl_add_u64 v[62:63], v[98:99], 0, s[16:17]
	v_lshlrev_b64 v[2:3], 12, v[66:67]
	v_lshlrev_b64 v[4:5], 12, v[4:5]
	v_lshlrev_b64 v[10:11], 12, v[10:11]
	v_lshlrev_b64 v[12:13], 12, v[12:13]
	v_lshlrev_b64 v[18:19], 12, v[18:19]
	v_lshlrev_b64 v[20:21], 12, v[20:21]
	v_lshlrev_b64 v[26:27], 12, v[26:27]
	v_lshlrev_b64 v[28:29], 12, v[28:29]
	v_lshlrev_b64 v[34:35], 12, v[34:35]
	v_lshlrev_b64 v[36:37], 12, v[36:37]
	v_lshlrev_b64 v[42:43], 12, v[42:43]
	v_lshlrev_b64 v[44:45], 12, v[44:45]
	v_lshlrev_b64 v[50:51], 12, v[50:51]
	v_lshlrev_b64 v[52:53], 12, v[52:53]
	v_lshl_add_u64 v[2:3], v[62:63], 0, v[2:3]
	v_lshl_add_u64 v[6:7], v[62:63], 0, v[4:5]
	v_lshl_add_u64 v[10:11], v[62:63], 0, v[10:11]
	v_lshl_add_u64 v[14:15], v[62:63], 0, v[12:13]
	v_lshl_add_u64 v[18:19], v[62:63], 0, v[18:19]
	v_lshl_add_u64 v[22:23], v[62:63], 0, v[20:21]
	v_lshl_add_u64 v[26:27], v[62:63], 0, v[26:27]
	v_lshl_add_u64 v[30:31], v[62:63], 0, v[28:29]
	v_lshl_add_u64 v[34:35], v[62:63], 0, v[34:35]
	v_lshl_add_u64 v[38:39], v[62:63], 0, v[36:37]
	v_lshl_add_u64 v[42:43], v[62:63], 0, v[42:43]
	v_lshl_add_u64 v[46:47], v[62:63], 0, v[44:45]
	v_lshl_add_u64 v[50:51], v[62:63], 0, v[50:51]
	v_lshl_add_u64 v[54:55], v[62:63], 0, v[52:53]
	global_load_dwordx4 v[2:5], v[2:3], off nt
	s_nop 0
	global_load_dwordx4 v[6:9], v[6:7], off nt
	s_nop 0
	global_load_dwordx4 v[10:13], v[10:11], off nt
	s_nop 0
	global_load_dwordx4 v[14:17], v[14:15], off nt
	s_nop 0
	global_load_dwordx4 v[18:21], v[18:19], off nt
	s_nop 0
	global_load_dwordx4 v[22:25], v[22:23], off nt
	s_nop 0
	global_load_dwordx4 v[26:29], v[26:27], off nt
	s_nop 0
	global_load_dwordx4 v[30:33], v[30:31], off nt
	s_nop 0
	global_load_dwordx4 v[34:37], v[34:35], off nt
	s_nop 0
	global_load_dwordx4 v[38:41], v[38:39], off nt
	s_nop 0
	global_load_dwordx4 v[42:45], v[42:43], off nt
	s_nop 0
	global_load_dwordx4 v[46:49], v[46:47], off nt
	s_nop 0
	global_load_dwordx4 v[50:53], v[50:51], off nt
	s_nop 0
	global_load_dwordx4 v[54:57], v[54:55], off nt
	v_or_b32_e32 v58, 56, v66
	v_mov_b32_e32 v59, v67
	v_lshlrev_b64 v[58:59], 12, v[58:59]
	v_lshl_add_u64 v[58:59], v[62:63], 0, v[58:59]
	v_or_b32_e32 v66, 60, v66
	global_load_dwordx4 v[58:61], v[58:59], off nt
	v_lshlrev_b64 v[64:65], 12, v[66:67]
	v_lshl_add_u64 v[62:63], v[62:63], 0, v[64:65]
	global_load_dwordx4 v[62:65], v[62:63], off nt
	s_lshl_b32 s16, s3, 1
	s_waitcnt vmcnt(15)
	ds_write2_b32 v103, v2, v3 offset1:1
	ds_write2_b32 v103, v4, v5 offset0:2 offset1:3
	s_waitcnt vmcnt(14)
	ds_write2_b32 v125, v6, v7 offset1:1
	ds_write2_b32 v126, v8, v9 offset1:1
	s_waitcnt vmcnt(13)
	ds_write2_b32 v127, v10, v11 offset1:1
	ds_write2_b32 v128, v12, v13 offset1:1
	s_waitcnt vmcnt(12)
	ds_write2_b32 v129, v14, v15 offset1:1
	ds_write2_b32 v130, v16, v17 offset1:1
	s_waitcnt vmcnt(11)
	ds_write2_b32 v131, v18, v19 offset1:1
	ds_write2_b32 v132, v20, v21 offset1:1
	s_waitcnt vmcnt(10)
	ds_write2_b32 v133, v22, v23 offset1:1
	ds_write2_b32 v134, v24, v25 offset1:1
	s_waitcnt vmcnt(9)
	ds_write2_b32 v135, v26, v27 offset1:1
	ds_write2_b32 v136, v28, v29 offset1:1
	s_waitcnt vmcnt(8)
	ds_write2_b32 v137, v30, v31 offset1:1
	ds_write2_b32 v138, v32, v33 offset1:1
	s_waitcnt vmcnt(7)
	ds_write2_b32 v139, v34, v35 offset1:1
	ds_write2_b32 v140, v36, v37 offset1:1
	s_waitcnt vmcnt(6)
	ds_write2_b32 v141, v38, v39 offset1:1
	ds_write2_b32 v142, v40, v41 offset1:1
	s_waitcnt vmcnt(5)
	ds_write2_b32 v143, v42, v43 offset1:1
	ds_write2_b32 v144, v44, v45 offset1:1
	s_waitcnt vmcnt(4)
	ds_write2_b32 v145, v46, v47 offset1:1
	ds_write2_b32 v146, v48, v49 offset1:1
	s_waitcnt vmcnt(3)
	ds_write2_b32 v147, v50, v51 offset1:1
	ds_write2_b32 v148, v52, v53 offset1:1
	s_waitcnt vmcnt(2)
; __device__ __forceinline__ unsigned pk2(float lo, float hi) { f32x2_t v = {lo, hi}; bf16x2_t b = __builtin_convertvector(v, bf16x2_t); return __builtin_bit_cast(unsigned, b); }
; #define TRY(W, K, N, WT, gain) { const int nt_ = ((K) / 64) * ((N) / 64); if (r >= 0 && r < nt_) { const int nb_ = (N) / 64; transpose_tile(W, K, N, WT, gain, (r / nb_) * 64, (r % nb_) * 64, tile, C.lane); } r -= nt_; }
; __device__ __forceinline__ void transpose_tile(const float* W, int K, int N, bf16* WT, const float* gain, int k0, int n0, LAS float* tile, int lane) {
;     ...
;     for (int pass = 0; pass < 8; ++pass) {
;         const int n = pass * 8 + (lane >> 3), kc = (lane & 7) * 8;
;         float f[8];
; #pragma unroll
;         for (int q = 0; q < 8; ++q) f[q] = tile[(kc + q) * 65 + n];
;         u32x4 o; o.x = pk2(f[0], f[1]); o.y = pk2(f[2], f[3]); o.z = pk2(f[4], f[5]); o.w = pk2(f[6], f[7]);
;         *(u32x4*)(WT + (size_t)(n0 + n) * K + k0 + kc) = o;
;     }
;     asm volatile("s_waitcnt lgkmcnt(0)" ::: "memory"); __builtin_amdgcn_wave_barrier();
; __device__ __forceinline__ void p0_prologue(const Ctx& C) {
;     ...
;         TRY(C.in[27], 4096, 1024, WSP(bf16, WS_WDN), (const float*)nullptr)
	ds_write2_b32 v149, v54, v55 offset1:1
	ds_write2_b32 v150, v56, v57 offset1:1
	s_waitcnt vmcnt(1)
	ds_write2_b32 v151, v58, v59 offset1:1
	ds_write2_b32 v152, v60, v61 offset1:1
	s_waitcnt vmcnt(0)
	ds_write2_b32 v153, v62, v63 offset1:1
	ds_write2_b32 v154, v64, v65 offset1:1
	s_waitcnt lgkmcnt(0)
	ds_read2_b32 v[6:7], v116 offset0:65 offset1:73
	ds_read2_b32 v[8:9], v116 offset1:8
	ds_read2_b32 v[10:11], v116 offset0:130 offset1:138
	ds_read2_b32 v[12:13], v116 offset0:195 offset1:203
	ds_read2_b32 v[14:15], v124 offset0:4 offset1:12
	ds_read2_b32 v[16:17], v124 offset0:69 offset1:77
	ds_read2_b32 v[18:19], v124 offset0:134 offset1:142
	ds_read2_b32 v[20:21], v124 offset0:199 offset1:207
	s_waitcnt lgkmcnt(6)
	v_cvt_pk_bf16_f32 v2, v8, v6
	v_or_b32_e32 v6, s2, v115
	v_lshl_add_u64 v[22:23], v[82:83], 0, s[16:17]
	v_lshlrev_b32_e32 v66, 13, v6
	s_waitcnt lgkmcnt(4)
	v_cvt_pk_bf16_f32 v3, v10, v12
	s_waitcnt lgkmcnt(2)
	v_cvt_pk_bf16_f32 v4, v14, v16
	s_waitcnt lgkmcnt(0)
	v_cvt_pk_bf16_f32 v5, v18, v20
	v_lshl_add_u64 v[24:25], v[22:23], 0, v[66:67]
	global_store_dwordx4 v[24:25], v[2:5], off
	v_or_b32_e32 v6, s2, v117
	v_lshlrev_b32_e32 v66, 13, v6
	v_cvt_pk_bf16_f32 v2, v9, v7
	v_cvt_pk_bf16_f32 v3, v11, v13
	v_cvt_pk_bf16_f32 v4, v15, v17
	v_cvt_pk_bf16_f32 v5, v19, v21
	ds_read2_b32 v[8:9], v116 offset0:81 offset1:89
	ds_read2_b32 v[10:11], v116 offset0:16 offset1:24
	ds_read2_b32 v[12:13], v116 offset0:146 offset1:154
	ds_read2_b32 v[14:15], v116 offset0:211 offset1:219
	ds_read2_b32 v[16:17], v124 offset0:20 offset1:28
	ds_read2_b32 v[18:19], v124 offset0:85 offset1:93
	ds_read2_b32 v[20:21], v124 offset0:150 offset1:158
	ds_read2_b32 v[24:25], v124 offset0:215 offset1:223
	v_lshl_add_u64 v[6:7], v[22:23], 0, v[66:67]
	global_store_dwordx4 v[6:7], v[2:5], off
	v_or_b32_e32 v6, s2, v118
	v_lshlrev_b32_e32 v66, 13, v6
	s_waitcnt lgkmcnt(6)
	v_cvt_pk_bf16_f32 v2, v10, v8
	s_waitcnt lgkmcnt(4)
	v_cvt_pk_bf16_f32 v3, v12, v14
	s_waitcnt lgkmcnt(2)
	v_cvt_pk_bf16_f32 v4, v16, v18
	s_waitcnt lgkmcnt(0)
	v_cvt_pk_bf16_f32 v5, v20, v24
	v_lshl_add_u64 v[6:7], v[22:23], 0, v[66:67]
	global_store_dwordx4 v[6:7], v[2:5], off
	v_or_b32_e32 v6, s2, v119
	v_lshlrev_b32_e32 v66, 13, v6
	v_cvt_pk_bf16_f32 v2, v11, v9
	v_cvt_pk_bf16_f32 v3, v13, v15
	v_cvt_pk_bf16_f32 v4, v17, v19
	v_cvt_pk_bf16_f32 v5, v21, v25
	ds_read2_b32 v[8:9], v116 offset0:32 offset1:40
	ds_read2_b32 v[10:11], v116 offset0:97 offset1:105
	ds_read2_b32 v[12:13], v116 offset0:162 offset1:170
	ds_read2_b32 v[14:15], v116 offset0:227 offset1:235
	ds_read2_b32 v[16:17], v124 offset0:36 offset1:44
	ds_read2_b32 v[18:19], v124 offset0:101 offset1:109
	ds_read2_b32 v[20:21], v124 offset0:166 offset1:174
	ds_read2_b32 v[24:25], v124 offset0:231 offset1:239
	v_lshl_add_u64 v[6:7], v[22:23], 0, v[66:67]
	global_store_dwordx4 v[6:7], v[2:5], off
	v_or_b32_e32 v6, s2, v120
	v_lshlrev_b32_e32 v66, 13, v6
	s_waitcnt lgkmcnt(6)
	v_cvt_pk_bf16_f32 v2, v8, v10
	s_waitcnt lgkmcnt(4)
	v_cvt_pk_bf16_f32 v3, v12, v14
	s_waitcnt lgkmcnt(2)
	v_cvt_pk_bf16_f32 v4, v16, v18
	s_waitcnt lgkmcnt(0)
	v_cvt_pk_bf16_f32 v5, v20, v24
	v_lshl_add_u64 v[6:7], v[22:23], 0, v[66:67]
	global_store_dwordx4 v[6:7], v[2:5], off
	v_or_b32_e32 v6, s2, v121
	v_lshlrev_b32_e32 v66, 13, v6
	v_cvt_pk_bf16_f32 v2, v9, v11
	v_cvt_pk_bf16_f32 v3, v13, v15
	v_cvt_pk_bf16_f32 v4, v17, v19
	v_cvt_pk_bf16_f32 v5, v21, v25
	ds_read2_b32 v[8:9], v116 offset0:48 offset1:56
	ds_read2_b32 v[10:11], v116 offset0:113 offset1:121
	ds_read2_b32 v[12:13], v116 offset0:178 offset1:186
	ds_read2_b32 v[14:15], v116 offset0:243 offset1:251
	ds_read2_b32 v[16:17], v124 offset0:52 offset1:60
	ds_read2_b32 v[18:19], v124 offset0:117 offset1:125
	ds_read2_b32 v[20:21], v124 offset0:182 offset1:190
	ds_read2_b32 v[24:25], v124 offset0:247 offset1:255
	v_lshl_add_u64 v[6:7], v[22:23], 0, v[66:67]
	global_store_dwordx4 v[6:7], v[2:5], off
	v_or_b32_e32 v6, s2, v122
	v_lshlrev_b32_e32 v66, 13, v6
	s_waitcnt lgkmcnt(6)
	v_cvt_pk_bf16_f32 v2, v8, v10
	s_waitcnt lgkmcnt(4)
	v_cvt_pk_bf16_f32 v3, v12, v14
	s_waitcnt lgkmcnt(2)
	v_cvt_pk_bf16_f32 v4, v16, v18
	s_waitcnt lgkmcnt(0)
	v_cvt_pk_bf16_f32 v5, v20, v24
	v_lshl_add_u64 v[6:7], v[22:23], 0, v[66:67]
	global_store_dwordx4 v[6:7], v[2:5], off
	v_or_b32_e32 v6, s2, v123
	v_lshlrev_b32_e32 v66, 13, v6
	v_cvt_pk_bf16_f32 v2, v9, v11
	v_cvt_pk_bf16_f32 v3, v13, v15
	v_cvt_pk_bf16_f32 v4, v17, v19
	v_cvt_pk_bf16_f32 v5, v21, v25
	v_lshl_add_u64 v[6:7], v[22:23], 0, v[66:67]
	global_store_dwordx4 v[6:7], v[2:5], off
	s_waitcnt lgkmcnt(0)
	s_branch .LBB0_7

; __device__ __forceinline__ void p0_prologue(const Ctx& C) {
;     ...
;     for (int m = C.gw; m < T; m += 2 * C.NGW) {
;         const int m2 = m + C.NGW;
;         const float* x0 = C.in[0] + (size_t)m * 1024; const float* x1 = C.in[0] + (size_t)(m2 < T ? m2 : m) * 1024;
;         f32x4 v[4], w[4]; float s0 = 0.f, s1 = 0.f;
; #pragma unroll
;         for (int j = 0; j < 4; ++j) { v[j] = ((const f32x4*)x0)[C.lane + 64 * j]; w[j] = ((const f32x4*)x1)[C.lane + 64 * j]; }
; #pragma unroll
;         for (int j = 0; j < 4; ++j) { s0 += (v[j].x * v[j].x + v[j].y * v[j].y) + (v[j].z * v[j].z + v[j].w * v[j].w); s1 += (w[j].x * w[j].x + w[j].y * w[j].y) + (w[j].z * w[j].z + w[j].w * w[j].w); }
;         s0 = wave_sum(s0); s1 = wave_sum(s1);
;         if (C.lane == 0) WSP(float, WS_RS0)[m] = rsqrtf(s0 * (1.f / 1024.f) + EPS);
.LBB0_188:
	s_add_i32 s0, s22, s34
	s_ashr_i32 s23, s22, 31
	s_cmp_lt_i32 s0, 0x8000
	s_cselect_b64 s[16:17], -1, 0
	s_and_b64 s[24:25], s[16:17], exec
	s_cselect_b32 s24, s0, s22
	s_lshl_b64 s[28:29], s[22:23], 12
	v_lshl_add_u64 v[2:3], v[36:37], 0, s[28:29]
	s_ashr_i32 s25, s24, 31
	global_load_dwordx4 v[30:33], v[2:3], off nt
	global_load_dwordx4 v[26:29], v[2:3], off offset:1024 nt
	global_load_dwordx4 v[22:25], v[2:3], off offset:2048 nt
	global_load_dwordx4 v[18:21], v[2:3], off offset:3072 nt
	s_lshl_b64 s[24:25], s[24:25], 12
	v_lshl_add_u64 v[2:3], v[36:37], 0, s[24:25]
	global_load_dwordx4 v[14:17], v[2:3], off nt
	global_load_dwordx4 v[10:13], v[2:3], off offset:1024 nt
	global_load_dwordx4 v[6:9], v[2:3], off offset:2048 nt
	s_nop 0
	global_load_dwordx4 v[2:5], v[2:3], off offset:3072 nt
	s_waitcnt vmcnt(7)
	v_mul_f32_e32 v44, v31, v31
	s_waitcnt lgkmcnt(0)
	v_mul_f32_e32 v45, v33, v33
	s_waitcnt vmcnt(6)
	v_mul_f32_e32 v46, v27, v27
	v_mul_f32_e32 v47, v29, v29
	s_waitcnt vmcnt(5)
	v_mul_f32_e32 v48, v23, v23
	v_mul_f32_e32 v49, v25, v25
	v_fmac_f32_e32 v44, v30, v30
	v_fmac_f32_e32 v45, v32, v32
	v_fmac_f32_e32 v46, v26, v26
	v_fmac_f32_e32 v47, v28, v28
	s_waitcnt vmcnt(4)
	v_mul_f32_e32 v50, v19, v19
	v_mul_f32_e32 v51, v21, v21
	v_fmac_f32_e32 v48, v22, v22
	v_fmac_f32_e32 v49, v24, v24
	v_add_f32_e32 v44, v44, v45
	s_waitcnt vmcnt(3)
	v_mul_f32_e32 v45, v15, v15
	v_mul_f32_e32 v52, v17, v17
	v_add_f32_e32 v46, v46, v47
	s_waitcnt vmcnt(2)
	v_mul_f32_e32 v47, v11, v11
	v_mul_f32_e32 v53, v13, v13
	v_fmac_f32_e32 v50, v18, v18
	v_fmac_f32_e32 v51, v20, v20
	v_add_f32_e32 v48, v48, v49
	s_waitcnt vmcnt(1)
	v_mul_f32_e32 v49, v7, v7
	v_mul_f32_e32 v54, v9, v9
	v_fmac_f32_e32 v45, v14, v14
	v_fmac_f32_e32 v52, v16, v16
	v_fmac_f32_e32 v47, v10, v10
	v_fmac_f32_e32 v53, v12, v12
	v_add_f32_e32 v50, v50, v51
	s_waitcnt vmcnt(0)
	v_mul_f32_e32 v51, v3, v3
	v_mul_f32_e32 v55, v5, v5
	v_add_f32_e32 v44, v44, v46
	v_fmac_f32_e32 v49, v6, v6
	v_fmac_f32_e32 v54, v8, v8
	v_add_f32_e32 v45, v45, v52
	v_add_f32_e32 v46, v47, v53
	v_fmac_f32_e32 v51, v2, v2
	v_fmac_f32_e32 v55, v4, v4
	v_add_f32_e32 v47, v49, v54
	v_add_f32_e32 v45, v45, v46
	v_add_f32_e32 v44, v44, v48
	v_add_f32_e32 v48, v51, v55
	v_add_f32_e32 v45, v45, v47
	v_add_f32_e32 v44, v44, v50
	v_add_f32_e32 v45, v45, v48
	ds_bpermute_b32 v46, v1, v44
	ds_bpermute_b32 v47, v1, v45
	s_waitcnt lgkmcnt(1)
	v_add_f32_e32 v44, v44, v46
	s_waitcnt lgkmcnt(0)
	v_add_f32_e32 v45, v45, v47
	ds_bpermute_b32 v46, v38, v44
	ds_bpermute_b32 v47, v38, v45
	s_waitcnt lgkmcnt(1)
	v_add_f32_e32 v44, v44, v46
	s_waitcnt lgkmcnt(0)
	v_add_f32_e32 v45, v45, v47
	ds_bpermute_b32 v46, v39, v44
	ds_bpermute_b32 v47, v39, v45
	s_waitcnt lgkmcnt(1)
	v_add_f32_e32 v44, v44, v46
	s_waitcnt lgkmcnt(0)
	v_add_f32_e32 v45, v45, v47
	ds_bpermute_b32 v46, v40, v44
	ds_bpermute_b32 v47, v40, v45
	s_waitcnt lgkmcnt(1)
	v_add_f32_e32 v44, v44, v46
	s_waitcnt lgkmcnt(0)
	v_add_f32_e32 v45, v45, v47
	ds_bpermute_b32 v46, v41, v44
	ds_bpermute_b32 v48, v41, v45
	s_waitcnt lgkmcnt(1)
	v_add_f32_e32 v46, v44, v46
	s_waitcnt lgkmcnt(0)
	v_add_f32_e32 v44, v45, v48
	ds_bpermute_b32 v47, v42, v46
	ds_bpermute_b32 v45, v42, v44
	s_and_saveexec_b64 s[24:25], s[2:3]
	s_cbranch_execz .LBB0_190
	s_waitcnt lgkmcnt(1)
	v_add_f32_e32 v46, v46, v47
	v_fmamk_f32 v46, v46, 0x3a800000, v43
	v_mul_f32_e32 v47, 0x4b800000, v46
	v_cmp_gt_f32_e32 vcc, s27, v46
	s_lshl_b64 s[28:29], s[22:23], 2
	s_add_u32 s28, s7, s28
	v_cndmask_b32_e32 v46, v46, v47, vcc
	v_rsq_f32_e32 v46, v46
	s_addc_u32 s29, s26, s29
	v_mul_f32_e32 v47, 0x45800000, v46
	v_cndmask_b32_e32 v46, v46, v47, vcc
	global_store_dword v129, v46, s[28:29]

; __device__ __forceinline__ void row_to_bf16(const float* xrow, bf16* orow, float* rs_out, int lane) {
;     f32x4 v[4]; float s = 0.f;
; #pragma unroll
;     for (int j = 0; j < 4; ++j) { v[j] = ((const f32x4*)xrow)[lane + 64 * j]; s += (v[j].x * v[j].x + v[j].y * v[j].y) + (v[j].z * v[j].z + v[j].w * v[j].w); }
;     s = wave_sum(s);
;     if (lane == 0) *rs_out = rsqrtf(s * (1.f / 1024.f) + EPS);
; __device__ __forceinline__ void p0_prologue(const Ctx& C) {
;     ...
;     for (int mm = C.gw; mm < 1024; mm += C.NGW) row_to_bf16(C.in[1] + (size_t)mm * 1024, WSP(bf16, WS_MEMB) + (size_t)mm * 1024, WSP(float, WS_RSM) + mm, C.lane);
.LBB0_198:
	global_load_dwordx4 v[6:9], v[22:23], off offset:-3072 nt
	global_load_dwordx4 v[2:5], v[22:23], off offset:-2048 nt
	global_load_dwordx4 v[10:13], v[22:23], off offset:-1024 nt
	global_load_dwordx4 v[14:17], v[22:23], off nt
	s_waitcnt vmcnt(3)
	v_mul_f32_e32 v29, v7, v7
	s_waitcnt lgkmcnt(0)
	v_mul_f32_e32 v30, v9, v9
	s_waitcnt vmcnt(2)
	v_mul_f32_e32 v31, v3, v3
	v_mul_f32_e32 v32, v5, v5
	s_waitcnt vmcnt(1)
	v_mul_f32_e32 v33, v11, v11
	v_mul_f32_e32 v34, v13, v13
	v_fmac_f32_e32 v29, v6, v6
	v_fmac_f32_e32 v30, v8, v8
	v_fmac_f32_e32 v31, v2, v2
	v_fmac_f32_e32 v32, v4, v4
	s_waitcnt vmcnt(0)
	v_mul_f32_e32 v35, v15, v15
	v_mul_f32_e32 v36, v17, v17
	v_fmac_f32_e32 v33, v10, v10
	v_fmac_f32_e32 v34, v12, v12
	v_add_f32_e32 v29, v29, v30
	v_add_f32_e32 v30, v31, v32
	v_fmac_f32_e32 v35, v14, v14
	v_fmac_f32_e32 v36, v16, v16
	v_add_f32_e32 v31, v33, v34
	v_add_f32_e32 v29, v29, v30
	v_add_f32_e32 v29, v29, v31
	v_add_f32_e32 v30, v35, v36
	v_add_f32_e32 v29, v29, v30
	ds_bpermute_b32 v30, v1, v29
	s_waitcnt lgkmcnt(0)
	v_add_f32_e32 v29, v29, v30
	ds_bpermute_b32 v30, v24, v29
	s_waitcnt lgkmcnt(0)
	v_add_f32_e32 v29, v29, v30
	ds_bpermute_b32 v30, v25, v29
	s_waitcnt lgkmcnt(0)
	v_add_f32_e32 v29, v29, v30
	ds_bpermute_b32 v30, v26, v29
	s_waitcnt lgkmcnt(0)
	v_add_f32_e32 v29, v29, v30
	ds_bpermute_b32 v30, v27, v29
	s_waitcnt lgkmcnt(0)
	v_add_f32_e32 v29, v29, v30
	ds_bpermute_b32 v30, v28, v29
	s_and_saveexec_b64 s[22:23], s[2:3]
	s_cbranch_execz .LBB0_197
	s_waitcnt lgkmcnt(0)
	v_add_f32_e32 v29, v29, v30
	v_fmamk_f32 v29, v29, 0x3a800000, v20
	v_mul_f32_e32 v30, 0x4b800000, v29
	v_cmp_gt_f32_e32 vcc, s7, v29
	s_add_u32 s28, s78, s24
	s_addc_u32 s29, s79, s25
	v_cndmask_b32_e32 v29, v29, v30, vcc
	v_rsq_f32_e32 v29, v29
	s_nop 0
	v_mul_f32_e32 v30, 0x45800000, v29
	v_cndmask_b32_e32 v29, v29, v30, vcc
	global_store_dword v21, v29, s[28:29]
	s_branch .LBB0_197

; __device__ __forceinline__ unsigned pk2(float lo, float hi) { f32x2_t v = {lo, hi}; bf16x2_t b = __builtin_convertvector(v, bf16x2_t); return __builtin_bit_cast(unsigned, b); }
; __device__ __forceinline__ void p2_prep(const Ctx& C0) {
;     ...
;         for (int tk0 = C.gw; tk0 < T; tk0 += 2 * C.NGW) {
;             u32x4 qv[2], kv[2];
; #pragma unroll
;             for (int u = 0; u < 2; ++u) {
;                 const int tk = (tk0 + u * C.NGW < T) ? tk0 + u * C.NGW : tk0;
;                 const bf16* pr = PROJ + (size_t)tk * 2048;
;                 qv[u] = *(const u32x4*)(pr + 512 + 8 * lane); kv[u] = *(const u32x4*)(pr + 1024 + 8 * lane);
;             }
; #pragma unroll
;             for (int u = 0; u < 2; ++u) {
;                 const int tk = tk0 + u * C.NGW;
;                 if (tk < T) {
;                     const int b = tk >> 13, s = tk & 8191;
;                     float q[8] = {bflo(qv[u].x), bfhi(qv[u].x), bflo(qv[u].y), bfhi(qv[u].y), bflo(qv[u].z), bfhi(qv[u].z), bflo(qv[u].w), bfhi(qv[u].w)};
;                     float k[8] = {bflo(kv[u].x), bfhi(kv[u].x), bflo(kv[u].y), bfhi(kv[u].y), bflo(kv[u].z), bfhi(kv[u].z), bflo(kv[u].w), bfhi(kv[u].w)};
;                     float sq = 0.f, sk = 0.f;
; #pragma unroll
;                     for (int j = 0; j < 8; ++j) { sq += q[j] * q[j]; sk += k[j] * k[j]; }
; #pragma unroll
;                     for (int o = 1; o < 8; o <<= 1) { sq += __shfl_xor(sq, o); sk += __shfl_xor(sk, o); }
;                     const float rq = rsqrtf(sq * (1.f / 64.f) + EPS), rk = rsqrtf(sk * (1.f / 64.f) + EPS);
; #pragma unroll
;                     for (int j = 0; j < 8; ++j) { q[j] *= rq * gqv[j]; k[j] *= rk * gkv[j]; }
;                     const size_t dst = ((size_t)(b * 8 + h) * 8192 + s) * 64 + d0;
;                     u32x4 o; o.x = pk2(q[0], q[1]); o.y = pk2(q[2], q[3]); o.z = pk2(q[4], q[5]); o.w = pk2(q[6], q[7]);
;                     *(u32x4*)(WSP(bf16, WS_QN) + dst) = o;
;                     o.x = pk2(k[0], k[1]); o.y = pk2(k[2], k[3]); o.z = pk2(k[4], k[5]); o.w = pk2(k[6], k[7]);
;                     *(u32x4*)(WSP(bf16, WS_KN) + dst) = o;
.LBB0_382:
	s_add_i32 s23, s0, s22
	s_cmp_lt_i32 s23, 0x8000
	s_cselect_b32 s24, s23, s0
	s_ashr_i32 s1, s0, 31
	s_lshl_b64 s[26:27], s[0:1], 12
	s_waitcnt vmcnt(2)
	v_lshl_add_u64 v[8:9], v[18:19], 0, s[26:27]
	global_load_dwordx4 v[32:35], v[8:9], off offset:1024 nt
	global_load_dwordx4 v[36:39], v[8:9], off offset:2048 nt
	s_ashr_i32 s25, s24, 31
	s_lshl_b64 s[24:25], s[24:25], 12
	v_lshl_add_u64 v[8:9], v[18:19], 0, s[24:25]
	global_load_dwordx4 v[12:15], v[8:9], off offset:1024 nt
	s_nop 0
	global_load_dwordx4 v[8:11], v[8:9], off offset:2048 nt
	s_ashr_i32 s0, s0, 10
	s_and_b32 s1, s19, 0x7ffc0
	s_cmpk_gt_i32 s23, 0x7fff
	s_waitcnt vmcnt(3)
	v_lshlrev_b32_e32 v44, 16, v32
	v_and_b32_e32 v45, 0xffff0000, v32
	s_waitcnt vmcnt(2)
	v_lshlrev_b32_e32 v48, 16, v36
	v_and_b32_e32 v49, 0xffff0000, v36
	v_lshlrev_b32_e32 v40, 16, v35
	v_and_b32_e32 v41, 0xffff0000, v35
	v_lshlrev_b32_e32 v42, 16, v34
	v_and_b32_e32 v43, 0xffff0000, v34
	v_lshlrev_b32_e32 v34, 16, v33
	v_and_b32_e32 v35, 0xffff0000, v33
	v_lshlrev_b32_e32 v32, 16, v39
	v_and_b32_e32 v33, 0xffff0000, v39
	v_lshlrev_b32_e32 v46, 16, v38
	v_and_b32_e32 v47, 0xffff0000, v38
	v_lshlrev_b32_e32 v38, 16, v37
	v_and_b32_e32 v39, 0xffff0000, v37
	v_pk_mul_f32 v[54:55], v[44:45], v[44:45]
	v_pk_mul_f32 v[62:63], v[48:49], v[48:49]
	v_pk_mul_f32 v[52:53], v[34:35], v[34:35]
	v_pk_mul_f32 v[60:61], v[38:39], v[38:39]
	v_mov_b32_e32 v64, v62
	v_mov_b32_e32 v65, v54
	v_mov_b32_e32 v54, v63
	v_mov_b32_e32 v62, v60
	v_mov_b32_e32 v63, v52
	v_pk_add_f32 v[54:55], v[64:65], v[54:55]
	v_pk_mul_f32 v[50:51], v[42:43], v[42:43]
	v_pk_mul_f32 v[58:59], v[46:47], v[46:47]
	v_mov_b32_e32 v52, v61
	v_pk_add_f32 v[54:55], v[62:63], v[54:55]
	v_mov_b32_e32 v60, v58
	v_mov_b32_e32 v61, v50
	v_pk_add_f32 v[52:53], v[52:53], v[54:55]
	v_pk_mul_f32 v[36:37], v[40:41], v[40:41]
	v_pk_mul_f32 v[56:57], v[32:33], v[32:33]
	v_mov_b32_e32 v50, v59
	v_pk_add_f32 v[52:53], v[60:61], v[52:53]
	v_mov_b32_e32 v58, v56
	v_mov_b32_e32 v59, v36
	v_pk_add_f32 v[50:51], v[50:51], v[52:53]
	v_mov_b32_e32 v36, v57
	v_pk_add_f32 v[50:51], v[58:59], v[50:51]
	v_and_or_b32 v52, s0, -8, v17
	v_pk_add_f32 v[36:37], v[36:37], v[50:51]
	ds_bpermute_b32 v51, v29, v37
	ds_bpermute_b32 v50, v29, v36
	v_ashrrev_i32_e32 v53, 31, v52
	v_lshlrev_b64 v[52:53], 19, v[52:53]
	v_or_b32_e32 v52, s1, v52
	v_or_b32_e32 v52, v52, v16
	s_waitcnt lgkmcnt(0)
	v_pk_add_f32 v[36:37], v[36:37], v[50:51]
	ds_bpermute_b32 v51, v30, v37
	ds_bpermute_b32 v50, v30, v36
	v_lshlrev_b64 v[52:53], 1, v[52:53]
	s_waitcnt lgkmcnt(0)
	v_pk_add_f32 v[36:37], v[36:37], v[50:51]
	ds_bpermute_b32 v51, v31, v37
	ds_bpermute_b32 v50, v31, v36
	s_waitcnt lgkmcnt(0)
	v_pk_add_f32 v[36:37], v[36:37], v[50:51]
	s_nop 0
	v_pk_fma_f32 v[36:37], v[36:37], s[8:9], v[28:29] op_sel_hi:[1,0,0]
	s_nop 0
	v_mul_f32_e32 v50, 0x4b800000, v37
	v_cmp_gt_f32_e32 vcc, s18, v37
	v_mul_f32_e32 v51, 0x4b800000, v36
	v_cmp_gt_f32_e64 s[0:1], s18, v36
	v_cndmask_b32_e32 v37, v37, v50, vcc
	v_rsq_f32_e32 v37, v37
	v_cndmask_b32_e64 v36, v36, v51, s[0:1]
	v_rsq_f32_e32 v54, v36
	v_lshl_add_u64 v[50:51], s[4:5], 0, v[52:53]
	v_mul_f32_e32 v36, 0x45800000, v37
	v_cndmask_b32_e32 v36, v37, v36, vcc
	v_mul_f32_e32 v55, 0x45800000, v54
	v_cndmask_b32_e64 v54, v54, v55, s[0:1]
	v_pk_mul_f32 v[56:57], v[20:21], v[36:37] op_sel_hi:[1,0]
	v_pk_mul_f32 v[58:59], v[22:23], v[36:37] op_sel_hi:[1,0]
	v_pk_mul_f32 v[60:61], v[24:25], v[36:37] op_sel_hi:[1,0]
	v_pk_mul_f32 v[36:37], v[26:27], v[36:37] op_sel_hi:[1,0]
	v_pk_mul_f32 v[62:63], v[4:5], v[54:55] op_sel_hi:[1,0]
	v_pk_mul_f32 v[64:65], v[6:7], v[54:55] op_sel_hi:[1,0]
	v_pk_mul_f32 v[66:67], v[0:1], v[54:55] op_sel_hi:[1,0]
	v_pk_mul_f32 v[54:55], v[2:3], v[54:55] op_sel_hi:[1,0]
	v_pk_mul_f32 v[44:45], v[56:57], v[44:45]
	v_pk_mul_f32 v[34:35], v[58:59], v[34:35]
	v_pk_mul_f32 v[42:43], v[60:61], v[42:43]
	v_pk_mul_f32 v[36:37], v[36:37], v[40:41]
	v_pk_mul_f32 v[40:41], v[62:63], v[48:49]
	v_pk_mul_f32 v[38:39], v[64:65], v[38:39]
	v_pk_mul_f32 v[46:47], v[66:67], v[46:47]
	v_pk_mul_f32 v[48:49], v[54:55], v[32:33]
	v_cvt_pk_bf16_f32 v32, v44, v45
	v_cvt_pk_bf16_f32 v33, v34, v35
	v_cvt_pk_bf16_f32 v34, v42, v43
	v_cvt_pk_bf16_f32 v35, v36, v37
	v_lshl_add_u64 v[52:53], s[16:17], 0, v[52:53]
	v_cvt_pk_bf16_f32 v36, v40, v41
	v_cvt_pk_bf16_f32 v37, v38, v39
	v_cvt_pk_bf16_f32 v38, v46, v47
	v_cvt_pk_bf16_f32 v39, v48, v49
	global_store_dwordx4 v[50:51], v[32:35], off
	global_store_dwordx4 v[52:53], v[36:39], off
	s_cbranch_scc1 .LBB0_381
; __device__ __forceinline__ unsigned pk2(float lo, float hi) { f32x2_t v = {lo, hi}; bf16x2_t b = __builtin_convertvector(v, bf16x2_t); return __builtin_bit_cast(unsigned, b); }
; __device__ __forceinline__ void p2_prep(const Ctx& C0) {
;     ...
;             for (int u = 0; u < 2; ++u) {
;                 const int tk = tk0 + u * C.NGW;
;                 if (tk < T) {
;                     const int b = tk >> 13, s = tk & 8191;
;                     float q[8] = {bflo(qv[u].x), bfhi(qv[u].x), bflo(qv[u].y), bfhi(qv[u].y), bflo(qv[u].z), bfhi(qv[u].z), bflo(qv[u].w), bfhi(qv[u].w)};
;                     float k[8] = {bflo(kv[u].x), bfhi(kv[u].x), bflo(kv[u].y), bfhi(kv[u].y), bflo(kv[u].z), bfhi(kv[u].z), bflo(kv[u].w), bfhi(kv[u].w)};
;                     float sq = 0.f, sk = 0.f;
; #pragma unroll
;                     for (int j = 0; j < 8; ++j) { sq += q[j] * q[j]; sk += k[j] * k[j]; }
; #pragma unroll
;                     for (int o = 1; o < 8; o <<= 1) { sq += __shfl_xor(sq, o); sk += __shfl_xor(sk, o); }
;                     const float rq = rsqrtf(sq * (1.f / 64.f) + EPS), rk = rsqrtf(sk * (1.f / 64.f) + EPS);
; #pragma unroll
;                     for (int j = 0; j < 8; ++j) { q[j] *= rq * gqv[j]; k[j] *= rk * gkv[j]; }
;                     const size_t dst = ((size_t)(b * 8 + h) * 8192 + s) * 64 + d0;
;                     u32x4 o; o.x = pk2(q[0], q[1]); o.y = pk2(q[2], q[3]); o.z = pk2(q[4], q[5]); o.w = pk2(q[6], q[7]);
;                     *(u32x4*)(WSP(bf16, WS_QN) + dst) = o;
;                     o.x = pk2(k[0], k[1]); o.y = pk2(k[2], k[3]); o.z = pk2(k[4], k[5]); o.w = pk2(k[6], k[7]);
;                     *(u32x4*)(WSP(bf16, WS_KN) + dst) = o;
	s_waitcnt vmcnt(3)
	v_lshlrev_b32_e32 v42, 16, v12
	v_and_b32_e32 v43, 0xffff0000, v12
	s_waitcnt vmcnt(2)
	v_lshlrev_b32_e32 v54, 16, v8
	v_and_b32_e32 v55, 0xffff0000, v8
	v_lshlrev_b32_e32 v38, 16, v13
	v_and_b32_e32 v39, 0xffff0000, v13
	v_pk_mul_f32 v[12:13], v[42:43], v[42:43]
	v_lshlrev_b32_e32 v50, 16, v9
	v_and_b32_e32 v51, 0xffff0000, v9
	v_pk_mul_f32 v[8:9], v[54:55], v[54:55]
	v_pk_mul_f32 v[40:41], v[38:39], v[38:39]
	v_pk_mul_f32 v[52:53], v[50:51], v[50:51]
	v_mov_b32_e32 v56, v8
	v_mov_b32_e32 v57, v12
	v_mov_b32_e32 v12, v9
	v_lshlrev_b32_e32 v36, 16, v14
	v_and_b32_e32 v37, 0xffff0000, v14
	v_lshlrev_b32_e32 v48, 16, v10
	v_and_b32_e32 v49, 0xffff0000, v10
	v_pk_add_f32 v[8:9], v[56:57], v[12:13]
	v_mov_b32_e32 v12, v52
	v_mov_b32_e32 v13, v40
	v_lshlrev_b32_e32 v32, 16, v15
	v_and_b32_e32 v33, 0xffff0000, v15
	v_pk_mul_f32 v[14:15], v[36:37], v[36:37]
	v_lshlrev_b32_e32 v44, 16, v11
	v_and_b32_e32 v45, 0xffff0000, v11
	v_pk_mul_f32 v[10:11], v[48:49], v[48:49]
	v_pk_add_f32 v[8:9], v[12:13], v[8:9]
	v_mov_b32_e32 v40, v53
	v_pk_add_f32 v[8:9], v[40:41], v[8:9]
	v_mov_b32_e32 v12, v10
	v_mov_b32_e32 v13, v14
	v_pk_mul_f32 v[34:35], v[32:33], v[32:33]
	v_pk_mul_f32 v[46:47], v[44:45], v[44:45]
	v_pk_add_f32 v[8:9], v[12:13], v[8:9]
	v_mov_b32_e32 v14, v11
	v_pk_add_f32 v[8:9], v[14:15], v[8:9]
	v_mov_b32_e32 v10, v46
	v_mov_b32_e32 v11, v34
	v_pk_add_f32 v[8:9], v[10:11], v[8:9]
	v_mov_b32_e32 v34, v47
	v_pk_add_f32 v[8:9], v[34:35], v[8:9]
	ds_bpermute_b32 v11, v29, v9
	ds_bpermute_b32 v10, v29, v8
	s_ashr_i32 s0, s23, 10
	s_waitcnt lgkmcnt(0)
	v_pk_add_f32 v[8:9], v[8:9], v[10:11]
	ds_bpermute_b32 v11, v30, v9
	ds_bpermute_b32 v10, v30, v8
	s_waitcnt lgkmcnt(0)
	v_pk_add_f32 v[8:9], v[8:9], v[10:11]
	ds_bpermute_b32 v11, v31, v9
	ds_bpermute_b32 v10, v31, v8
	s_waitcnt lgkmcnt(0)
	v_pk_add_f32 v[8:9], v[8:9], v[10:11]
	s_nop 0
	v_pk_fma_f32 v[8:9], v[8:9], s[8:9], v[28:29] op_sel_hi:[1,0,0]
	s_nop 0
	v_mul_f32_e32 v10, 0x4b800000, v9
	v_cmp_gt_f32_e32 vcc, s18, v9
	s_nop 1
	v_cndmask_b32_e32 v9, v9, v10, vcc
	v_rsq_f32_e32 v9, v9
	s_nop 0
	v_mul_f32_e32 v10, 0x45800000, v9
	v_cndmask_b32_e32 v10, v9, v10, vcc
	v_mul_f32_e32 v9, 0x4b800000, v8
	v_cmp_gt_f32_e32 vcc, s18, v8
	v_pk_mul_f32 v[12:13], v[20:21], v[10:11] op_sel_hi:[1,0]
	v_pk_mul_f32 v[14:15], v[22:23], v[10:11] op_sel_hi:[1,0]
	v_cndmask_b32_e32 v8, v8, v9, vcc
	v_pk_mul_f32 v[34:35], v[24:25], v[10:11] op_sel_hi:[1,0]
	v_rsq_f32_e32 v11, v8
	v_pk_mul_f32 v[34:35], v[34:35], v[36:37]
	v_pk_mul_f32 v[14:15], v[14:15], v[38:39]
	v_pk_mul_f32 v[12:13], v[12:13], v[42:43]
	v_pk_mul_f32 v[8:9], v[26:27], v[10:11] op_sel_hi:[1,0]
	s_nop 0
	v_pk_mul_f32 v[32:33], v[8:9], v[32:33]
	v_mul_f32_e32 v8, 0x45800000, v11
	v_cndmask_b32_e32 v8, v11, v8, vcc
	v_pk_mul_f32 v[10:11], v[4:5], v[8:9] op_sel_hi:[1,0]
	s_nop 0
	v_pk_mul_f32 v[36:37], v[10:11], v[54:55]
	v_pk_mul_f32 v[10:11], v[6:7], v[8:9] op_sel_hi:[1,0]
	s_nop 0
	v_pk_mul_f32 v[38:39], v[10:11], v[50:51]
	v_pk_mul_f32 v[10:11], v[0:1], v[8:9] op_sel_hi:[1,0]
	v_pk_mul_f32 v[8:9], v[2:3], v[8:9] op_sel_hi:[1,0]
	v_pk_mul_f32 v[40:41], v[10:11], v[48:49]
	v_pk_mul_f32 v[42:43], v[8:9], v[44:45]
	v_and_or_b32 v8, s0, -8, v17
	v_ashrrev_i32_e32 v9, 31, v8
	s_add_i32 s0, s21, s19
	v_lshlrev_b64 v[44:45], 19, v[8:9]
	s_and_b32 s0, s0, 0x7ffc0
	v_or_b32_e32 v8, s0, v44
	v_or_b32_e32 v44, v8, v16
	v_cvt_pk_bf16_f32 v8, v12, v13
	v_lshlrev_b64 v[12:13], 1, v[44:45]
	v_cvt_pk_bf16_f32 v9, v14, v15
	v_cvt_pk_bf16_f32 v10, v34, v35
	v_cvt_pk_bf16_f32 v11, v32, v33
	v_lshl_add_u64 v[14:15], s[4:5], 0, v[12:13]
	global_store_dwordx4 v[14:15], v[8:11], off
	v_lshl_add_u64 v[12:13], s[16:17], 0, v[12:13]
	s_nop 0
	v_cvt_pk_bf16_f32 v8, v36, v37
	v_cvt_pk_bf16_f32 v9, v38, v39
	v_cvt_pk_bf16_f32 v10, v40, v41
	v_cvt_pk_bf16_f32 v11, v42, v43
	global_store_dwordx4 v[12:13], v[8:11], off
	s_branch .LBB0_381

; #define LAS __attribute__((address_space(3)))
; __device__ __forceinline__ void p2_prep(const Ctx& C0) {
;     ...
;         for (int it = C.bid; it < 512; it += C.G) {
;             const int b = it >> 7, s0 = (it & 127) * 64;
; #pragma unroll
;             for (int i = 0; i < 8; ++i) {
;                 const int chunk = tid + 512 * i, row = chunk >> 6, cc = (chunk & 63) * 8;
;                 const u32x4 v = *(const u32x4*)(PROJ + (size_t)(b * 8192 + s0 + row) * 2048 + 1536 + cc);
;                 LAS unsigned* d = (LAS unsigned*)(vt + row * 514 + cc);
;                 d[0] = v.x; d[1] = v.y; d[2] = v.z; d[3] = v.w;
;             }
;             __syncthreads();
;             bf16* dst = WSP(bf16, WS_VT) + ((size_t)(b * 8 + (tid >> 6)) * 64 + (tid & 63)) * 8192 + s0;
; #pragma unroll
;             for (int j8 = 0; j8 < 8; ++j8) {
;                 unsigned e[8];
; #pragma unroll
;                 for (int q = 0; q < 8; ++q) e[q] = vt[(8 * j8 + q) * 514 + tid];
;                 u32x4 o; o.x = e[0] | (e[1] << 16); o.y = e[2] | (e[3] << 16); o.z = e[4] | (e[5] << 16); o.w = e[6] | (e[7] << 16);
;                 *(u32x4*)(dst + 8 * j8) = o;
;             }
;             __syncthreads();
.LBB0_386:
	s_ashr_i32 s0, s7, 7
	s_and_b32 s8, s4, 0x1fc0
	s_lshl_b32 s16, s0, 13
	v_lshl_add_u32 v24, s0, 3, v4
	s_lshl_b32 s0, s8, 1
	s_or_b32 s8, s16, s8
	v_or_b32_e32 v26, s8, v4
	v_ashrrev_i32_e32 v25, 31, v24
	v_or_b32_e32 v28, s8, v6
	v_or_b32_e32 v30, s8, v7
	v_or_b32_e32 v32, s8, v8
	v_or_b32_e32 v34, s8, v9
	v_or_b32_e32 v36, s8, v10
	v_or_b32_e32 v38, s8, v11
	v_add_u32_e32 v40, s8, v12
	v_ashrrev_i32_e32 v27, 31, v26
	v_lshlrev_b64 v[24:25], 20, v[24:25]
	v_ashrrev_i32_e32 v29, 31, v28
	v_ashrrev_i32_e32 v31, 31, v30
	v_ashrrev_i32_e32 v33, 31, v32
	v_ashrrev_i32_e32 v35, 31, v34
	v_ashrrev_i32_e32 v37, 31, v36
	v_ashrrev_i32_e32 v39, 31, v38
	v_ashrrev_i32_e32 v41, 31, v40
	v_lshlrev_b64 v[26:27], 12, v[26:27]
	v_lshl_add_u64 v[24:25], v[0:1], 0, v[24:25]
	v_lshlrev_b64 v[28:29], 12, v[28:29]
	v_lshlrev_b64 v[30:31], 12, v[30:31]
	v_lshlrev_b64 v[32:33], 12, v[32:33]
	v_lshlrev_b64 v[34:35], 12, v[34:35]
	v_lshlrev_b64 v[36:37], 12, v[36:37]
	v_lshlrev_b64 v[38:39], 12, v[38:39]
	v_lshlrev_b64 v[40:41], 12, v[40:41]
	v_lshl_add_u64 v[58:59], v[2:3], 0, v[26:27]
	v_lshl_add_u64 v[56:57], v[24:25], 0, s[0:1]
	v_lshl_add_u64 v[60:61], v[2:3], 0, v[28:29]
	v_lshl_add_u64 v[62:63], v[2:3], 0, v[30:31]
	v_lshl_add_u64 v[64:65], v[2:3], 0, v[32:33]
	v_lshl_add_u64 v[66:67], v[2:3], 0, v[34:35]
	v_lshl_add_u64 v[68:69], v[2:3], 0, v[36:37]
	v_lshl_add_u64 v[70:71], v[2:3], 0, v[38:39]
	v_lshl_add_u64 v[72:73], v[2:3], 0, v[40:41]
	global_load_dwordx4 v[24:27], v[58:59], off offset:3072 nt
	global_load_dwordx4 v[28:31], v[60:61], off offset:3072 nt
	global_load_dwordx4 v[32:35], v[62:63], off offset:3072 nt
	global_load_dwordx4 v[36:39], v[64:65], off offset:3072 nt
	global_load_dwordx4 v[40:43], v[66:67], off offset:3072 nt
	global_load_dwordx4 v[44:47], v[68:69], off offset:3072 nt
	global_load_dwordx4 v[48:51], v[70:71], off offset:3072 nt
	global_load_dwordx4 v[52:55], v[72:73], off offset:3072 nt
	s_add_i32 s7, s7, s9
	s_add_i32 s4, s4, s5
	s_cmpk_lt_i32 s7, 0x200
	s_waitcnt vmcnt(7)
	ds_write2_b32 v13, v24, v25 offset1:1
	ds_write2_b32 v13, v26, v27 offset0:2 offset1:3
	s_waitcnt vmcnt(6)
	ds_write2_b32 v14, v28, v29 offset1:1
	ds_write2_b32 v14, v30, v31 offset0:2 offset1:3
	s_waitcnt vmcnt(5)
	ds_write2_b32 v15, v32, v33 offset1:1
	ds_write2_b32 v16, v34, v35 offset1:1
	s_waitcnt vmcnt(4)
	ds_write2_b32 v17, v36, v37 offset1:1
	ds_write2_b32 v17, v38, v39 offset0:2 offset1:3
	s_waitcnt vmcnt(3)
	ds_write2_b32 v18, v40, v41 offset1:1
	ds_write2_b32 v19, v42, v43 offset1:1
	s_waitcnt vmcnt(2)
	ds_write2_b32 v20, v44, v45 offset1:1
	ds_write2_b32 v20, v46, v47 offset0:2 offset1:3
	s_waitcnt vmcnt(1)
	ds_write2_b32 v21, v48, v49 offset1:1
	ds_write2_b32 v22, v50, v51 offset1:1
	s_waitcnt vmcnt(0)
	ds_write2_b32 v23, v52, v53 offset1:1
	ds_write2_b32 v23, v54, v55 offset0:2 offset1:3
	s_waitcnt lgkmcnt(0)
	s_barrier
	ds_read_u16 v24, v5
	ds_read_u16 v25, v5 offset:1028
	ds_read_u16 v26, v5 offset:2056
	ds_read_u16 v27, v5 offset:3084
	ds_read_u16 v28, v5 offset:4112
	ds_read_u16 v29, v5 offset:5140
	ds_read_u16 v30, v5 offset:6168
	ds_read_u16 v31, v5 offset:7196
	ds_read_u16 v32, v5 offset:8224
	ds_read_u16 v33, v5 offset:9252
	ds_read_u16 v34, v5 offset:10280
	ds_read_u16 v35, v5 offset:11308
	ds_read_u16 v36, v5 offset:12336
	ds_read_u16 v37, v5 offset:13364
	ds_read_u16 v38, v5 offset:14392
	ds_read_u16 v39, v5 offset:15420
	ds_read_u16 v40, v5 offset:16448
	ds_read_u16 v41, v5 offset:17476
	ds_read_u16 v42, v5 offset:18504
	ds_read_u16 v43, v5 offset:19532
	ds_read_u16 v44, v5 offset:20560
	ds_read_u16 v45, v5 offset:21588
	ds_read_u16 v46, v5 offset:22616
	ds_read_u16 v47, v5 offset:23644
	ds_read_u16 v48, v5 offset:24672
	ds_read_u16 v49, v5 offset:25700
	ds_read_u16 v50, v5 offset:26728
	ds_read_u16 v51, v5 offset:27756
	ds_read_u16 v52, v5 offset:28784
	ds_read_u16 v53, v5 offset:29812
	ds_read_u16 v54, v5 offset:30840
	ds_read_u16 v55, v5 offset:31868
	ds_read_u16 v58, v5 offset:32896
	ds_read_u16 v59, v5 offset:33924
	ds_read_u16 v60, v5 offset:34952
	ds_read_u16 v61, v5 offset:35980
	ds_read_u16 v62, v5 offset:37008
	ds_read_u16 v63, v5 offset:38036
	ds_read_u16 v64, v5 offset:39064
	ds_read_u16 v65, v5 offset:40092
	ds_read_u16 v66, v5 offset:41120
	ds_read_u16 v67, v5 offset:42148
	ds_read_u16 v68, v5 offset:43176
	ds_read_u16 v69, v5 offset:44204
	ds_read_u16 v70, v5 offset:45232
	ds_read_u16 v71, v5 offset:46260
	ds_read_u16 v72, v5 offset:47288
	ds_read_u16 v73, v5 offset:48316
	ds_read_u16 v74, v5 offset:49344
	ds_read_u16 v75, v5 offset:50372
	ds_read_u16 v76, v5 offset:51400
	ds_read_u16 v77, v5 offset:52428
	ds_read_u16 v78, v5 offset:53456
	ds_read_u16 v79, v5 offset:54484
	ds_read_u16 v80, v5 offset:55512
	ds_read_u16 v81, v5 offset:56540
	ds_read_u16 v82, v5 offset:57568
	ds_read_u16 v83, v5 offset:58596
	ds_read_u16 v84, v5 offset:59624
	ds_read_u16 v85, v5 offset:60652
	ds_read_u16 v86, v5 offset:61680
	ds_read_u16 v87, v5 offset:62708
	ds_read_u16 v88, v5 offset:63736
	ds_read_u16 v89, v5 offset:64764
	s_waitcnt lgkmcnt(14)
	v_lshl_or_b32 v24, v25, 16, v24
	v_lshl_or_b32 v25, v27, 16, v26
	v_lshl_or_b32 v26, v29, 16, v28
	v_lshl_or_b32 v27, v31, 16, v30
	v_lshl_or_b32 v28, v33, 16, v32
	v_lshl_or_b32 v29, v35, 16, v34
	v_lshl_or_b32 v30, v37, 16, v36
	v_lshl_or_b32 v31, v39, 16, v38
	v_lshl_or_b32 v32, v41, 16, v40
	v_lshl_or_b32 v33, v43, 16, v42
	v_lshl_or_b32 v34, v45, 16, v44
	v_lshl_or_b32 v35, v47, 16, v46
	v_lshl_or_b32 v36, v49, 16, v48
	v_lshl_or_b32 v37, v51, 16, v50
	v_lshl_or_b32 v38, v53, 16, v52
	v_lshl_or_b32 v39, v55, 16, v54
	v_lshl_or_b32 v40, v59, 16, v58
	v_lshl_or_b32 v41, v61, 16, v60
	v_lshl_or_b32 v42, v63, 16, v62
	v_lshl_or_b32 v43, v65, 16, v64
	v_lshl_or_b32 v44, v67, 16, v66
	v_lshl_or_b32 v45, v69, 16, v68
	v_lshl_or_b32 v46, v71, 16, v70
	v_lshl_or_b32 v47, v73, 16, v72
	v_lshl_or_b32 v48, v75, 16, v74
	s_waitcnt lgkmcnt(12)
	v_lshl_or_b32 v49, v77, 16, v76
	s_waitcnt lgkmcnt(10)
	v_lshl_or_b32 v50, v79, 16, v78
	s_waitcnt lgkmcnt(8)
	v_lshl_or_b32 v51, v81, 16, v80
	s_waitcnt lgkmcnt(6)
	v_lshl_or_b32 v52, v83, 16, v82
	s_waitcnt lgkmcnt(4)
	v_lshl_or_b32 v53, v85, 16, v84
	s_waitcnt lgkmcnt(2)
	v_lshl_or_b32 v54, v87, 16, v86
	s_waitcnt lgkmcnt(0)
	v_lshl_or_b32 v55, v89, 16, v88
	global_store_dwordx4 v[56:57], v[24:27], off
	global_store_dwordx4 v[56:57], v[28:31], off offset:16
	global_store_dwordx4 v[56:57], v[32:35], off offset:32
	global_store_dwordx4 v[56:57], v[36:39], off offset:48
	global_store_dwordx4 v[56:57], v[40:43], off offset:64
	global_store_dwordx4 v[56:57], v[44:47], off offset:80
	global_store_dwordx4 v[56:57], v[48:51], off offset:96
	global_store_dwordx4 v[56:57], v[52:55], off offset:112
	s_barrier
	s_cbranch_scc1 .LBB0_386

; #define LAS __attribute__((address_space(3)))
; template <bool ATOM> __device__ __forceinline__ void sb_fast(const Ctx& C) {
;     ...
;     for (int item = C.bid; item < 512; item += C.G) {
;         const int bh = item & 31, pp = item >> 5, b = bh >> 3, h = bh & 7;
;         const bf16* kbase = KN + (size_t)bh * SEQ * 64 + lrow * 64 + lchunk * 8;
;         const bf16* vbase = VT + (size_t)bh * 64 * SEQ + (size_t)lrow * SEQ + lchunk * 8;
; #pragma unroll 1
;         for (int half = 0; half < 2; ++half) {
;             const int qb = half ? pp : 31 - pp;
;             const int tw0 = qb * 256 + wave * 32, t = tw0 + l32;
;             bf16x8 qf[4];
;             {
;                 const bf16* qp = QN + ((size_t)bh * SEQ + t) * 64 + 8 * hf;
; #pragma unroll
;                 for (int kk = 0; kk < 4; ++kk) qf[kk] = *(const bf16x8*)(qp + 16 * kk);
;                 asm volatile("" : "+v"(qf[0]), "+v"(qf[1]), "+v"(qf[2]), "+v"(qf[3]));
;             }
;             f32x16 o0, o1;
; #pragma unroll
;             for (int r = 0; r < 16; ++r) { o0[r] = 0.f; o1[r] = 0.f; }
;             float R = 1.f;
;             int jt = 4 * qb + 3;
;             u32x4 kreg = *(const u32x4*)(kbase + (size_t)jt * 4096);
;             u32x4 vreg = *(const u32x4*)(vbase + jt * 64);
;             *(LAS u32x4*)(lds + ldoff) = kreg; *(LAS u32x4*)(lds + 9216 + ldoff) = vreg;
;             __syncthreads();
;             int cur = 0;
;             bool wdone = false;
; #pragma unroll 1
;     ...
;                 if (jt > 0) { kreg = *(const u32x4*)(kbase + (size_t)(jt - 1) * 4096); vreg = *(const u32x4*)(vbase + (jt - 1) * 64); }
.LBB0_482:
	s_and_b64 s[60:61], s[58:59], exec
	s_cselect_b32 s64, s82, s75
	s_lshl_b32 s55, s64, 8
	s_add_i32 s84, s55, s66
	v_or_b32_e32 v114, s84, v201
	v_ashrrev_i32_e32 v115, 31, v114
	v_lshlrev_b64 v[0:1], 7, v[114:115]
	v_lshl_add_u64 v[0:1], v[112:113], 0, v[0:1]
	global_load_dwordx4 v[64:67], v[0:1], off offset:96 nt
	global_load_dwordx4 v[68:71], v[0:1], off offset:64 nt
	global_load_dwordx4 v[72:75], v[0:1], off offset:32 nt
	global_load_dwordx4 v[76:79], v[0:1], off nt
	s_lshl_b32 s48, s64, 2
	s_or_b32 s60, s48, 3
	s_ashr_i32 s61, s60, 31
	s_lshl_b32 s62, s60, 6
	s_lshl_b64 s[60:61], s[60:61], 13
	s_ashr_i32 s63, s62, 31
	v_lshl_add_u64 v[0:1], v[108:109], 0, s[60:61]
	v_lshl_add_u64 v[2:3], s[62:63], 1, v[110:111]
	s_cmp_lt_i32 s64, 0
	s_waitcnt vmcnt(0)
	global_load_dwordx4 v[88:91], v[0:1], off nt
	global_load_dwordx4 v[92:95], v[2:3], off nt
	s_waitcnt vmcnt(1)
	ds_write_b128 v103, v[88:91]
	s_waitcnt vmcnt(0)
	ds_write_b128 v103, v[92:95] offset:9216
	s_waitcnt lgkmcnt(0)
	s_barrier
	s_cbranch_scc1 .LBB0_508
	v_mov_b32_e32 v14, v97
	v_mov_b32_e32 v15, v97
	v_mov_b32_e32 v0, v97
	v_mov_b32_e32 v1, v97
	v_mov_b32_e32 v2, v97
	v_mov_b32_e32 v3, v97
	v_mov_b32_e32 v4, v97
	v_mov_b32_e32 v5, v97
	v_mov_b32_e32 v6, v97
	v_mov_b32_e32 v7, v97
	v_mov_b32_e32 v8, v97
	v_mov_b32_e32 v9, v97
	v_mov_b32_e32 v10, v97
	v_mov_b32_e32 v11, v97
	v_mov_b32_e32 v12, v97
	v_mov_b32_e32 v13, v97
	v_mov_b64_e32 v[30:31], v[14:15]
	s_add_i32 s85, s48, 4
	v_mov_b32_e32 v117, 1.0
	s_mov_b64 s[62:63], 0
	s_mov_b32 s86, 0
	s_mov_b32 s87, 0
	v_mov_b64_e32 v[28:29], v[12:13]
	v_mov_b64_e32 v[26:27], v[10:11]
	v_mov_b64_e32 v[24:25], v[8:9]
	v_mov_b64_e32 v[22:23], v[6:7]
	v_mov_b64_e32 v[20:21], v[4:5]
	v_mov_b64_e32 v[18:19], v[2:3]
	v_mov_b64_e32 v[16:17], v[0:1]
.LBB0_484:
	s_cmp_lg_u32 s85, 1
	s_cselect_b64 s[60:61], -1, 0
	s_mov_b64 s[64:65], -1
	s_and_b64 vcc, exec, s[60:61]
	s_cbranch_vccz .LBB0_486
	s_add_i32 s64, s85, -2
	s_mov_b32 s65, s49
	s_add_i32 s91, s55, s86
	s_lshl_b64 s[64:65], s[64:65], 13
	s_add_i32 s48, s91, 0x80
	v_lshl_add_u64 v[34:35], v[108:109], 0, s[64:65]
	v_lshl_add_u64 v[32:33], s[48:49], 1, v[110:111]
	global_load_dwordx4 v[84:87], v[34:35], off nt
	global_load_dwordx4 v[80:83], v[32:33], off nt
	s_mov_b64 s[64:65], 0
